# GEMM K-loops: MFMA order a0k0 a1k0 a0k1 a1k1 within each block
# baseline (speedup 1.0000x reference)
; #define PG8_STAGE(bufoff, gbase, voff) do { _Pragma("unroll") for (int _i = 0; _i < 2; ++_i) \
;         __builtin_amdgcn_global_load_lds((const unsigned*)((const char*)(gbase) + (voff)[_i]), (PG8_LAS unsigned*)(lds + (bufoff) + ldsw + _i * 8192), 16, 0, 0); } while (0)
; #define PG8_LDA(dst, b, h) do { _Pragma("unroll") for (int m = 0; m < 4; ++m) _Pragma("unroll") for (int k = 0; k < 2; ++k) dst[m][k] = *(const PG8_LAS bf16x8*)(lds + PG8_SA(b, h) + aoff + m * 2048 + k * 1024); } while (0)
; #define PG8_LDB(dst, b, h) do { _Pragma("unroll") for (int n = 0; n < 2; ++n) _Pragma("unroll") for (int k = 0; k < 2; ++k) dst[n][k] = *(const PG8_LAS bf16x8*)(lds + PG8_SB(b, h) + boff + n * 2048 + k * 1024); } while (0)
; #define PG8_MMA(ai, bj, At, Bt) do { __builtin_amdgcn_s_setprio(1); _Pragma("unroll") for (int m = 0; m < 4; ++m) _Pragma("unroll") for (int n = 0; n < 2; ++n) _Pragma("unroll") for (int k = 0; k < 2; ++k) \
;         acc[ai][bj][m][n] = __builtin_amdgcn_mfma_f32_16x16x32_bf16(Bt[n][k], At[m][k], acc[ai][bj][m][n], 0, 0, 0); __builtin_amdgcn_s_setprio(0); } while (0)
; #define PG8_WAIT_V(n) asm volatile("s_waitcnt vmcnt(" #n ")" ::: "memory")
; #define PG8_WAIT_L(n) asm volatile("s_waitcnt lgkmcnt(" #n ")" ::: "memory")
; #define PG8_BAR __builtin_amdgcn_s_barrier()
; #define PG8_SCHED __builtin_amdgcn_sched_barrier(0)
; template <class Epi, class Sched, bool ALIGN_EPI = false, bool SP2 = false>
; __device__ __forceinline__ void gemm_phase(PG8_LAS unsigned char* lds, const Gemm g, const Sched& S, const Epi& E) {
;     ...
;             const bool last = (t == nt - 2);
;             const char* a1 = cA + (size_t)(t + 1) * kstep;
;             const char* a2 = last ? nA : cA + (size_t)(t + 2) * kstep; const char* b2 = last ? nB : cB + (size_t)(t + 2) * kstep;
;             const char* a3 = a2 + kstep; const char* b3 = b2 + kstep;
;             if (last && has_next) S.a_ready(nxt);
;             if constexpr (SP2) {
;             PG8_LDB(B0, 0, 0); PG8_LDB(B1, 0, 1); PG8_SCHED; PG8_LDA(At, 0, 0); PG8_STAGE(PG8_SA(1, 1), a1 + hstep, voffA);
;             PG8_WAIT_V(8); PG8_WAIT_L(0); PG8_BAR; PG8_MMA(0, 0, At, B0); PG8_MMA(0, 1, At, B1); PG8_BAR; PG8_SCHED;
;             PG8_LDA(At, 0, 1); PG8_STAGE(PG8_SB(0, 0), b2, voffB); PG8_STAGE(PG8_SB(0, 1), b2 + hstep, voffB); PG8_STAGE(PG8_SA(0, 0), a2, voffA);
.LBB0_132:
	s_add_u32 s18, s46, 0xfffc0080
	s_addc_u32 s38, s47, -1
	s_add_i32 s39, 0, 0x10000
	s_cmp_eq_u32 s85, 12
	s_cselect_b32 s81, s33, s38
	s_cselect_b32 s80, s73, s18
	v_add_u32_e32 v0, s39, v176
	s_cselect_b32 s45, s75, s84
	s_cselect_b32 s44, s82, s83
	s_add_i32 s18, 0, 0x14000
	ds_read_b128 v[144:147], v0
	ds_read_b128 v[148:151], v0 offset:1024
	ds_read_b128 v[152:155], v0 offset:2048
	ds_read_b128 v[156:159], v0 offset:3072
	v_add_u32_e32 v0, s18, v176
	ds_read_b128 v[160:163], v0
	ds_read_b128 v[164:167], v0 offset:1024
	ds_read_b128 v[168:171], v0 offset:2048
	ds_read_b128 v[172:175], v0 offset:3072
	v_lshl_add_u64 v[218:219], s[46:47], 0, v[140:141]
	s_add_i32 m0, s92, 0xc000
	ds_read_b128 v[180:183], v178
	ds_read_b128 v[184:187], v178 offset:1024
	ds_read_b128 v[188:191], v178 offset:2048
	ds_read_b128 v[192:195], v178 offset:3072
	ds_read_b128 v[202:205], v178 offset:4096
	ds_read_b128 v[206:209], v178 offset:5120
	ds_read_b128 v[210:213], v178 offset:6144
	ds_read_b128 v[214:217], v178 offset:7168
	global_load_lds_dwordx4 v[218:219], off
	v_lshl_add_u64 v[218:219], s[46:47], 0, v[142:143]
	s_add_i32 m0, s92, 0xe000
	s_nop 0
	global_load_lds_dwordx4 v[218:219], off
	s_waitcnt vmcnt(8)
	s_waitcnt lgkmcnt(0)
	s_barrier
	s_setprio 1
	s_waitcnt lgkmcnt(0)
	v_mfma_f32_16x16x32_bf16 v[118:121], v[144:147], v[180:183], v[118:121]
	v_mfma_f32_16x16x32_bf16 v[114:117], v[152:155], v[180:183], v[114:117]
	v_mfma_f32_16x16x32_bf16 v[118:121], v[148:151], v[184:187], v[118:121]
	v_mfma_f32_16x16x32_bf16 v[114:117], v[156:159], v[184:187], v[114:117]
	v_mfma_f32_16x16x32_bf16 v[102:105], v[144:147], v[188:191], v[102:105]
	v_mfma_f32_16x16x32_bf16 v[98:101], v[152:155], v[188:191], v[98:101]
	v_mfma_f32_16x16x32_bf16 v[102:105], v[148:151], v[192:195], v[102:105]
	v_mfma_f32_16x16x32_bf16 v[98:101], v[156:159], v[192:195], v[98:101]
	v_mfma_f32_16x16x32_bf16 v[86:89], v[144:147], v[202:205], v[86:89]
	v_mfma_f32_16x16x32_bf16 v[82:85], v[152:155], v[202:205], v[82:85]
	v_mfma_f32_16x16x32_bf16 v[86:89], v[148:151], v[206:209], v[86:89]
	v_mfma_f32_16x16x32_bf16 v[82:85], v[156:159], v[206:209], v[82:85]
	v_mfma_f32_16x16x32_bf16 v[70:73], v[144:147], v[210:213], v[70:73]
	v_mfma_f32_16x16x32_bf16 v[66:69], v[152:155], v[210:213], v[66:69]
	v_mfma_f32_16x16x32_bf16 v[70:73], v[148:151], v[214:217], v[70:73]
	v_mfma_f32_16x16x32_bf16 v[66:69], v[156:159], v[214:217], v[66:69]
	s_setprio 0
	s_setprio 1
	v_mfma_f32_16x16x32_bf16 v[126:129], v[160:163], v[180:183], v[126:129]
	v_mfma_f32_16x16x32_bf16 v[122:125], v[168:171], v[180:183], v[122:125]
	v_mfma_f32_16x16x32_bf16 v[126:129], v[164:167], v[184:187], v[126:129]
	v_mfma_f32_16x16x32_bf16 v[122:125], v[172:175], v[184:187], v[122:125]
	v_mfma_f32_16x16x32_bf16 v[110:113], v[160:163], v[188:191], v[110:113]
	v_mfma_f32_16x16x32_bf16 v[106:109], v[168:171], v[188:191], v[106:109]
	v_mfma_f32_16x16x32_bf16 v[110:113], v[164:167], v[192:195], v[110:113]
	v_mfma_f32_16x16x32_bf16 v[106:109], v[172:175], v[192:195], v[106:109]
	v_mfma_f32_16x16x32_bf16 v[94:97], v[160:163], v[202:205], v[94:97]
	v_mfma_f32_16x16x32_bf16 v[90:93], v[168:171], v[202:205], v[90:93]
	v_mfma_f32_16x16x32_bf16 v[94:97], v[164:167], v[206:209], v[94:97]
	v_mfma_f32_16x16x32_bf16 v[90:93], v[172:175], v[206:209], v[90:93]
	v_mfma_f32_16x16x32_bf16 v[78:81], v[160:163], v[210:213], v[78:81]
	v_mfma_f32_16x16x32_bf16 v[74:77], v[168:171], v[210:213], v[74:77]
	v_mfma_f32_16x16x32_bf16 v[78:81], v[164:167], v[214:217], v[78:81]
	v_mfma_f32_16x16x32_bf16 v[74:77], v[172:175], v[214:217], v[74:77]
	s_setprio 0
	s_barrier
	s_add_i32 s38, s39, s91
	v_lshl_add_u64 v[218:219], s[44:45], 0, v[134:135]
	s_mov_b32 m0, s38
	ds_read_b128 v[180:183], v178 offset:16384
	ds_read_b128 v[184:187], v178 offset:17408
	ds_read_b128 v[188:191], v178 offset:18432
	ds_read_b128 v[192:195], v178 offset:19456
	ds_read_b128 v[202:205], v178 offset:20480
	ds_read_b128 v[206:209], v178 offset:21504
	ds_read_b128 v[210:213], v178 offset:22528
	ds_read_b128 v[214:217], v178 offset:23552
	global_load_lds_dwordx4 v[218:219], off
	s_add_i32 m0, s38, 0x2000
	s_add_u32 s38, s44, 0x40000
	v_lshl_add_u64 v[220:221], s[44:45], 0, v[130:131]
	s_addc_u32 s39, s45, 0
	s_add_i32 s18, s18, s91
	global_load_lds_dwordx4 v[220:221], off
	v_lshl_add_u64 v[222:223], s[38:39], 0, v[134:135]
	s_mov_b32 m0, s18
	v_lshl_add_u64 v[224:225], s[80:81], 0, v[132:133]
	global_load_lds_dwordx4 v[222:223], off
	v_lshl_add_u64 v[222:223], s[38:39], 0, v[130:131]
	s_add_i32 m0, s18, 0x2000
	s_nop 0
	global_load_lds_dwordx4 v[222:223], off
	v_lshl_add_u64 v[222:223], s[80:81], 0, v[136:137]
	s_mov_b32 m0, s92
	s_nop 0
	global_load_lds_dwordx4 v[222:223], off
	s_mov_b32 m0, s93
	s_nop 0
	global_load_lds_dwordx4 v[224:225], off
	s_waitcnt vmcnt(8)
	s_waitcnt lgkmcnt(0)
	s_barrier
; #define PG8_STAGE(bufoff, gbase, voff) do { _Pragma("unroll") for (int _i = 0; _i < 2; ++_i) \
;         __builtin_amdgcn_global_load_lds((const unsigned*)((const char*)(gbase) + (voff)[_i]), (PG8_LAS unsigned*)(lds + (bufoff) + ldsw + _i * 8192), 16, 0, 0); } while (0)
; #define PG8_LDA(dst, b, h) do { _Pragma("unroll") for (int m = 0; m < 4; ++m) _Pragma("unroll") for (int k = 0; k < 2; ++k) dst[m][k] = *(const PG8_LAS bf16x8*)(lds + PG8_SA(b, h) + aoff + m * 2048 + k * 1024); } while (0)
; #define PG8_LDB(dst, b, h) do { _Pragma("unroll") for (int n = 0; n < 2; ++n) _Pragma("unroll") for (int k = 0; k < 2; ++k) dst[n][k] = *(const PG8_LAS bf16x8*)(lds + PG8_SB(b, h) + boff + n * 2048 + k * 1024); } while (0)
; #define PG8_MMA(ai, bj, At, Bt) do { __builtin_amdgcn_s_setprio(1); _Pragma("unroll") for (int m = 0; m < 4; ++m) _Pragma("unroll") for (int n = 0; n < 2; ++n) _Pragma("unroll") for (int k = 0; k < 2; ++k) \
;         acc[ai][bj][m][n] = __builtin_amdgcn_mfma_f32_16x16x32_bf16(Bt[n][k], At[m][k], acc[ai][bj][m][n], 0, 0, 0); __builtin_amdgcn_s_setprio(0); } while (0)
; #define PG8_WAIT_V(n) asm volatile("s_waitcnt vmcnt(" #n ")" ::: "memory")
; #define PG8_WAIT_L(n) asm volatile("s_waitcnt lgkmcnt(" #n ")" ::: "memory")
; #define PG8_BAR __builtin_amdgcn_s_barrier()
; #define PG8_SCHED __builtin_amdgcn_sched_barrier(0)
; template <class Epi, class Sched, bool ALIGN_EPI = false, bool SP2 = false>
; __device__ __forceinline__ void gemm_phase(PG8_LAS unsigned char* lds, const Gemm g, const Sched& S, const Epi& E) {
;     ...
;             PG8_WAIT_V(8); PG8_WAIT_L(0); PG8_BAR; PG8_MMA(1, 0, At, B0); PG8_MMA(1, 1, At, B1); PG8_BAR; PG8_SCHED;
;             PG8_LDB(B0, 1, 0); PG8_LDB(B1, 1, 1); PG8_SCHED; PG8_LDA(At, 1, 0); PG8_STAGE(PG8_SA(0, 1), a2 + hstep, voffA);
;             PG8_WAIT_V(8); PG8_WAIT_L(0); PG8_BAR; PG8_MMA(0, 0, At, B0); PG8_MMA(0, 1, At, B1); PG8_BAR; PG8_SCHED;
	s_setprio 1
	s_waitcnt lgkmcnt(0)
	v_mfma_f32_16x16x32_bf16 v[54:57], v[144:147], v[180:183], v[54:57]
	v_mfma_f32_16x16x32_bf16 v[50:53], v[152:155], v[180:183], v[50:53]
	v_mfma_f32_16x16x32_bf16 v[54:57], v[148:151], v[184:187], v[54:57]
	v_mfma_f32_16x16x32_bf16 v[50:53], v[156:159], v[184:187], v[50:53]
	v_mfma_f32_16x16x32_bf16 v[38:41], v[144:147], v[188:191], v[38:41]
	v_mfma_f32_16x16x32_bf16 v[34:37], v[152:155], v[188:191], v[34:37]
	v_mfma_f32_16x16x32_bf16 v[38:41], v[148:151], v[192:195], v[38:41]
	v_mfma_f32_16x16x32_bf16 v[34:37], v[156:159], v[192:195], v[34:37]
	v_mfma_f32_16x16x32_bf16 v[22:25], v[144:147], v[202:205], v[22:25]
	v_mfma_f32_16x16x32_bf16 v[18:21], v[152:155], v[202:205], v[18:21]
	v_mfma_f32_16x16x32_bf16 v[22:25], v[148:151], v[206:209], v[22:25]
	v_mfma_f32_16x16x32_bf16 v[18:21], v[156:159], v[206:209], v[18:21]
	v_mfma_f32_16x16x32_bf16 v[6:9], v[144:147], v[210:213], v[6:9]
	v_mfma_f32_16x16x32_bf16 v[2:5], v[152:155], v[210:213], v[2:5]
	v_mfma_f32_16x16x32_bf16 v[6:9], v[148:151], v[214:217], v[6:9]
	v_mfma_f32_16x16x32_bf16 v[2:5], v[156:159], v[214:217], v[2:5]
	s_setprio 0
	s_setprio 1
	v_mfma_f32_16x16x32_bf16 v[62:65], v[160:163], v[180:183], v[62:65]
	v_mfma_f32_16x16x32_bf16 v[58:61], v[168:171], v[180:183], v[58:61]
	v_mfma_f32_16x16x32_bf16 v[62:65], v[164:167], v[184:187], v[62:65]
	v_mfma_f32_16x16x32_bf16 v[58:61], v[172:175], v[184:187], v[58:61]
	v_mfma_f32_16x16x32_bf16 v[46:49], v[160:163], v[188:191], v[46:49]
	v_mfma_f32_16x16x32_bf16 v[42:45], v[168:171], v[188:191], v[42:45]
	v_mfma_f32_16x16x32_bf16 v[46:49], v[164:167], v[192:195], v[46:49]
	v_mfma_f32_16x16x32_bf16 v[42:45], v[172:175], v[192:195], v[42:45]
	v_mfma_f32_16x16x32_bf16 v[30:33], v[160:163], v[202:205], v[30:33]
	v_mfma_f32_16x16x32_bf16 v[26:29], v[168:171], v[202:205], v[26:29]
	v_mfma_f32_16x16x32_bf16 v[30:33], v[164:167], v[206:209], v[30:33]
	v_mfma_f32_16x16x32_bf16 v[26:29], v[172:175], v[206:209], v[26:29]
	v_mfma_f32_16x16x32_bf16 v[10:13], v[160:163], v[210:213], v[10:13]
	v_mfma_f32_16x16x32_bf16 v[14:17], v[168:171], v[210:213], v[14:17]
	v_mfma_f32_16x16x32_bf16 v[10:13], v[164:167], v[214:217], v[10:13]
	v_mfma_f32_16x16x32_bf16 v[14:17], v[172:175], v[214:217], v[14:17]
	s_setprio 0
	s_barrier
	s_add_i32 s18, 0, 0x18000
	v_add_u32_e32 v0, s18, v176
	s_add_i32 vcc_lo, 0, 0x1c000
	ds_read_b128 v[144:147], v0
	ds_read_b128 v[148:151], v0 offset:1024
	ds_read_b128 v[152:155], v0 offset:2048
	ds_read_b128 v[156:159], v0 offset:3072
	v_add_u32_e32 v0, vcc_lo, v176
	ds_read_b128 v[160:163], v0
	ds_read_b128 v[164:167], v0 offset:1024
	ds_read_b128 v[168:171], v0 offset:2048
	ds_read_b128 v[172:175], v0 offset:3072
	s_add_u32 s38, s80, 0x40000
	s_addc_u32 s39, s81, 0
	s_mov_b32 m0, s94
	v_lshl_add_u64 v[226:227], s[38:39], 0, v[136:137]
	ds_read_b128 v[180:183], v178 offset:32768
	ds_read_b128 v[184:187], v178 offset:33792
	ds_read_b128 v[188:191], v178 offset:34816
	ds_read_b128 v[192:195], v178 offset:35840
	ds_read_b128 v[202:205], v178 offset:36864
	ds_read_b128 v[206:209], v178 offset:37888
	ds_read_b128 v[210:213], v178 offset:38912
	ds_read_b128 v[214:217], v178 offset:39936
	global_load_lds_dwordx4 v[226:227], off
	v_lshl_add_u64 v[226:227], s[38:39], 0, v[132:133]
	s_mov_b32 m0, s95
	s_nop 0
	global_load_lds_dwordx4 v[226:227], off
	s_waitcnt vmcnt(8)
	s_waitcnt lgkmcnt(0)
	s_barrier
	s_setprio 1
	s_waitcnt lgkmcnt(0)
	v_mfma_f32_16x16x32_bf16 v[118:121], v[144:147], v[180:183], v[118:121]
	v_mfma_f32_16x16x32_bf16 v[114:117], v[152:155], v[180:183], v[114:117]
	v_mfma_f32_16x16x32_bf16 v[118:121], v[148:151], v[184:187], v[118:121]
	v_mfma_f32_16x16x32_bf16 v[114:117], v[156:159], v[184:187], v[114:117]
	v_mfma_f32_16x16x32_bf16 v[102:105], v[144:147], v[188:191], v[102:105]
	v_mfma_f32_16x16x32_bf16 v[98:101], v[152:155], v[188:191], v[98:101]
	v_mfma_f32_16x16x32_bf16 v[102:105], v[148:151], v[192:195], v[102:105]
	v_mfma_f32_16x16x32_bf16 v[98:101], v[156:159], v[192:195], v[98:101]
	v_mfma_f32_16x16x32_bf16 v[86:89], v[144:147], v[202:205], v[86:89]
	v_mfma_f32_16x16x32_bf16 v[82:85], v[152:155], v[202:205], v[82:85]
	v_mfma_f32_16x16x32_bf16 v[86:89], v[148:151], v[206:209], v[86:89]
	v_mfma_f32_16x16x32_bf16 v[82:85], v[156:159], v[206:209], v[82:85]
	v_mfma_f32_16x16x32_bf16 v[70:73], v[144:147], v[210:213], v[70:73]
	v_mfma_f32_16x16x32_bf16 v[66:69], v[152:155], v[210:213], v[66:69]
	v_mfma_f32_16x16x32_bf16 v[70:73], v[148:151], v[214:217], v[70:73]
	v_mfma_f32_16x16x32_bf16 v[66:69], v[156:159], v[214:217], v[66:69]
	s_setprio 0
	s_setprio 1
	v_mfma_f32_16x16x32_bf16 v[126:129], v[160:163], v[180:183], v[126:129]
	v_mfma_f32_16x16x32_bf16 v[122:125], v[168:171], v[180:183], v[122:125]
	v_mfma_f32_16x16x32_bf16 v[126:129], v[164:167], v[184:187], v[126:129]
	v_mfma_f32_16x16x32_bf16 v[122:125], v[172:175], v[184:187], v[122:125]
	v_mfma_f32_16x16x32_bf16 v[110:113], v[160:163], v[188:191], v[110:113]
	v_mfma_f32_16x16x32_bf16 v[106:109], v[168:171], v[188:191], v[106:109]
	v_mfma_f32_16x16x32_bf16 v[110:113], v[164:167], v[192:195], v[110:113]
	v_mfma_f32_16x16x32_bf16 v[106:109], v[172:175], v[192:195], v[106:109]
	v_mfma_f32_16x16x32_bf16 v[94:97], v[160:163], v[202:205], v[94:97]
	v_mfma_f32_16x16x32_bf16 v[90:93], v[168:171], v[202:205], v[90:93]
	v_mfma_f32_16x16x32_bf16 v[94:97], v[164:167], v[206:209], v[94:97]
	v_mfma_f32_16x16x32_bf16 v[90:93], v[172:175], v[206:209], v[90:93]
	v_mfma_f32_16x16x32_bf16 v[78:81], v[160:163], v[210:213], v[78:81]
	v_mfma_f32_16x16x32_bf16 v[74:77], v[168:171], v[210:213], v[74:77]
	v_mfma_f32_16x16x32_bf16 v[78:81], v[164:167], v[214:217], v[78:81]
	v_mfma_f32_16x16x32_bf16 v[74:77], v[172:175], v[214:217], v[74:77]
	s_setprio 0
	s_barrier
; #define PG8_STAGE(bufoff, gbase, voff) do { _Pragma("unroll") for (int _i = 0; _i < 2; ++_i) \
;         __builtin_amdgcn_global_load_lds((const unsigned*)((const char*)(gbase) + (voff)[_i]), (PG8_LAS unsigned*)(lds + (bufoff) + ldsw + _i * 8192), 16, 0, 0); } while (0)
; #define PG8_LDA(dst, b, h) do { _Pragma("unroll") for (int m = 0; m < 4; ++m) _Pragma("unroll") for (int k = 0; k < 2; ++k) dst[m][k] = *(const PG8_LAS bf16x8*)(lds + PG8_SA(b, h) + aoff + m * 2048 + k * 1024); } while (0)
; #define PG8_MMA(ai, bj, At, Bt) do { __builtin_amdgcn_s_setprio(1); _Pragma("unroll") for (int m = 0; m < 4; ++m) _Pragma("unroll") for (int n = 0; n < 2; ++n) _Pragma("unroll") for (int k = 0; k < 2; ++k) \
;         acc[ai][bj][m][n] = __builtin_amdgcn_mfma_f32_16x16x32_bf16(Bt[n][k], At[m][k], acc[ai][bj][m][n], 0, 0, 0); __builtin_amdgcn_s_setprio(0); } while (0)
; #define PG8_WAIT_V(n) asm volatile("s_waitcnt vmcnt(" #n ")" ::: "memory")
; #define PG8_WAIT_L(n) asm volatile("s_waitcnt lgkmcnt(" #n ")" ::: "memory")
; #define PG8_BAR __builtin_amdgcn_s_barrier()
; #define PG8_SCHED __builtin_amdgcn_sched_barrier(0)
; template <class Epi, class Sched, bool ALIGN_EPI = false, bool SP2 = false>
; __device__ __forceinline__ void gemm_phase(PG8_LAS unsigned char* lds, const Gemm g, const Sched& S, const Epi& E) {
;     ...
;             PG8_LDA(At, 1, 1); PG8_STAGE(PG8_SB(1, 0), b3, voffB); PG8_STAGE(PG8_SB(1, 1), b3 + hstep, voffB); PG8_STAGE(PG8_SA(1, 0), a3, voffA);
;             PG8_WAIT_V(8); PG8_WAIT_L(0); PG8_BAR; PG8_MMA(1, 0, At, B0); PG8_MMA(1, 1, At, B1); PG8_BAR; PG8_SCHED;
	s_add_i32 s18, s18, s91
	v_lshl_add_u64 v[218:219], v[218:219], 0, s[30:31]
	s_mov_b32 m0, s18
	ds_read_b128 v[180:183], v178 offset:49152
	ds_read_b128 v[184:187], v178 offset:50176
	ds_read_b128 v[188:191], v178 offset:51200
	ds_read_b128 v[192:195], v178 offset:52224
	ds_read_b128 v[202:205], v178 offset:53248
	ds_read_b128 v[206:209], v178 offset:54272
	ds_read_b128 v[210:213], v178 offset:55296
	ds_read_b128 v[214:217], v178 offset:56320
	global_load_lds_dwordx4 v[218:219], off
	s_add_i32 m0, s18, 0x2000
	s_add_u32 s38, s44, 0x40080
	v_lshl_add_u64 v[218:219], v[220:221], 0, s[30:31]
	s_addc_u32 s39, s45, 0
	s_add_i32 s18, vcc_lo, s91
	global_load_lds_dwordx4 v[218:219], off
	v_lshl_add_u64 v[218:219], s[38:39], 0, v[134:135]
	s_mov_b32 m0, s18
	s_nop 0
	global_load_lds_dwordx4 v[218:219], off
	v_lshl_add_u64 v[218:219], s[38:39], 0, v[130:131]
	s_add_i32 m0, s18, 0x2000
	s_nop 0
	global_load_lds_dwordx4 v[218:219], off
	v_lshl_add_u64 v[218:219], v[222:223], 0, s[30:31]
	s_mov_b32 m0, s7
	s_nop 0
	global_load_lds_dwordx4 v[218:219], off
	v_lshl_add_u64 v[218:219], v[224:225], 0, s[30:31]
	s_mov_b32 m0, s96
	s_nop 0
	global_load_lds_dwordx4 v[218:219], off
	s_waitcnt vmcnt(8)
	s_waitcnt lgkmcnt(0)
	s_barrier
	s_setprio 1
	s_waitcnt lgkmcnt(0)
	v_mfma_f32_16x16x32_bf16 v[54:57], v[144:147], v[180:183], v[54:57]
	v_mfma_f32_16x16x32_bf16 v[50:53], v[152:155], v[180:183], v[50:53]
	v_mfma_f32_16x16x32_bf16 v[54:57], v[148:151], v[184:187], v[54:57]
	v_mfma_f32_16x16x32_bf16 v[50:53], v[156:159], v[184:187], v[50:53]
	v_mfma_f32_16x16x32_bf16 v[38:41], v[144:147], v[188:191], v[38:41]
	v_mfma_f32_16x16x32_bf16 v[34:37], v[152:155], v[188:191], v[34:37]
	v_mfma_f32_16x16x32_bf16 v[38:41], v[148:151], v[192:195], v[38:41]
	v_mfma_f32_16x16x32_bf16 v[34:37], v[156:159], v[192:195], v[34:37]
	v_mfma_f32_16x16x32_bf16 v[22:25], v[144:147], v[202:205], v[22:25]
	v_mfma_f32_16x16x32_bf16 v[18:21], v[152:155], v[202:205], v[18:21]
	v_mfma_f32_16x16x32_bf16 v[22:25], v[148:151], v[206:209], v[22:25]
	v_mfma_f32_16x16x32_bf16 v[18:21], v[156:159], v[206:209], v[18:21]
	v_mfma_f32_16x16x32_bf16 v[6:9], v[144:147], v[210:213], v[6:9]
	v_mfma_f32_16x16x32_bf16 v[2:5], v[152:155], v[210:213], v[2:5]
	v_mfma_f32_16x16x32_bf16 v[6:9], v[148:151], v[214:217], v[6:9]
	v_mfma_f32_16x16x32_bf16 v[2:5], v[156:159], v[214:217], v[2:5]
	s_setprio 0
	s_setprio 1
	v_mfma_f32_16x16x32_bf16 v[62:65], v[160:163], v[180:183], v[62:65]
	v_mfma_f32_16x16x32_bf16 v[58:61], v[168:171], v[180:183], v[58:61]
	v_mfma_f32_16x16x32_bf16 v[62:65], v[164:167], v[184:187], v[62:65]
	v_mfma_f32_16x16x32_bf16 v[58:61], v[172:175], v[184:187], v[58:61]
	v_mfma_f32_16x16x32_bf16 v[46:49], v[160:163], v[188:191], v[46:49]
	v_mfma_f32_16x16x32_bf16 v[42:45], v[168:171], v[188:191], v[42:45]
	v_mfma_f32_16x16x32_bf16 v[46:49], v[164:167], v[192:195], v[46:49]
	v_mfma_f32_16x16x32_bf16 v[42:45], v[172:175], v[192:195], v[42:45]
	v_mfma_f32_16x16x32_bf16 v[30:33], v[160:163], v[202:205], v[30:33]
	v_mfma_f32_16x16x32_bf16 v[26:29], v[168:171], v[202:205], v[26:29]
	v_mfma_f32_16x16x32_bf16 v[30:33], v[164:167], v[206:209], v[30:33]
	v_mfma_f32_16x16x32_bf16 v[26:29], v[172:175], v[206:209], v[26:29]
	v_mfma_f32_16x16x32_bf16 v[10:13], v[160:163], v[210:213], v[10:13]
	v_mfma_f32_16x16x32_bf16 v[14:17], v[168:171], v[210:213], v[14:17]
	v_mfma_f32_16x16x32_bf16 v[10:13], v[164:167], v[214:217], v[10:13]
	v_mfma_f32_16x16x32_bf16 v[14:17], v[172:175], v[214:217], v[14:17]
	s_setprio 0
	s_barrier
	s_add_i32 s85, s85, 2
	s_add_u32 s46, s46, 0x100
	s_addc_u32 s47, s47, 0
	s_add_u32 s83, s83, 0x100
	s_addc_u32 s84, s84, 0
	s_cmp_gt_u32 s85, 13
	s_cbranch_scc0 .LBB0_132
	s_and_b64 vcc, exec, s[10:11]
	s_cbranch_vccz .LBB0_135
	s_barrier

; #define PG8_STAGE(bufoff, gbase, voff) do { _Pragma("unroll") for (int _i = 0; _i < 2; ++_i) \
;         __builtin_amdgcn_global_load_lds((const unsigned*)((const char*)(gbase) + (voff)[_i]), (PG8_LAS unsigned*)(lds + (bufoff) + ldsw + _i * 8192), 16, 0, 0); } while (0)
; #define PG8_LDA(dst, b, h) do { _Pragma("unroll") for (int m = 0; m < 4; ++m) _Pragma("unroll") for (int k = 0; k < 2; ++k) dst[m][k] = *(const PG8_LAS bf16x8*)(lds + PG8_SA(b, h) + aoff + m * 2048 + k * 1024); } while (0)
; #define PG8_LDB(dst, b, h) do { _Pragma("unroll") for (int n = 0; n < 2; ++n) _Pragma("unroll") for (int k = 0; k < 2; ++k) dst[n][k] = *(const PG8_LAS bf16x8*)(lds + PG8_SB(b, h) + boff + n * 2048 + k * 1024); } while (0)
; #define PG8_MMA(ai, bj, At, Bt) do { __builtin_amdgcn_s_setprio(1); _Pragma("unroll") for (int m = 0; m < 4; ++m) _Pragma("unroll") for (int n = 0; n < 2; ++n) _Pragma("unroll") for (int k = 0; k < 2; ++k) \
;         acc[ai][bj][m][n] = __builtin_amdgcn_mfma_f32_16x16x32_bf16(Bt[n][k], At[m][k], acc[ai][bj][m][n], 0, 0, 0); __builtin_amdgcn_s_setprio(0); } while (0)
; #define PG8_WAIT_V(n) asm volatile("s_waitcnt vmcnt(" #n ")" ::: "memory")
; #define PG8_WAIT_L(n) asm volatile("s_waitcnt lgkmcnt(" #n ")" ::: "memory")
; #define PG8_BAR __builtin_amdgcn_s_barrier()
; #define PG8_SCHED __builtin_amdgcn_sched_barrier(0)
; template <class Epi, class Sched, bool ALIGN_EPI = false, bool SP2 = false>
; __device__ __forceinline__ void gemm_phase(PG8_LAS unsigned char* lds, const Gemm g, const Sched& S, const Epi& E) {
;     ...
;             const bool last = (t == nt - 2);
;             const char* a1 = cA + (size_t)(t + 1) * kstep;
;             const char* a2 = last ? nA : cA + (size_t)(t + 2) * kstep; const char* b2 = last ? nB : cB + (size_t)(t + 2) * kstep;
;             const char* a3 = a2 + kstep; const char* b3 = b2 + kstep;
;             if (last && has_next) S.a_ready(nxt);
;             if constexpr (SP2) {
;             PG8_LDB(B0, 0, 0); PG8_LDB(B1, 0, 1); PG8_SCHED; PG8_LDA(At, 0, 0); PG8_STAGE(PG8_SA(1, 1), a1 + hstep, voffA);
;             PG8_WAIT_V(8); PG8_WAIT_L(0); PG8_BAR; PG8_MMA(0, 0, At, B0); PG8_MMA(0, 1, At, B1); PG8_BAR; PG8_SCHED;
;             PG8_LDA(At, 0, 1); PG8_STAGE(PG8_SB(0, 0), b2, voffB); PG8_STAGE(PG8_SB(0, 1), b2 + hstep, voffB); PG8_STAGE(PG8_SA(0, 0), a2, voffA);
.LBB0_220:
	s_add_u32 s18, s60, 0xfffc0080
	s_addc_u32 s38, s61, -1
	s_add_i32 s39, 0, 0x10000
	s_cmp_eq_u32 s82, 12
	s_cselect_b32 s65, s47, s38
	s_cselect_b32 s64, s78, s18
	v_add_u32_e32 v145, s39, v141
	s_cselect_b32 s57, s49, s81
	s_cselect_b32 s56, s79, s80
	s_add_i32 s18, 0, 0x14000
	ds_read_b128 v[146:149], v145
	ds_read_b128 v[150:153], v145 offset:1024
	ds_read_b128 v[154:157], v145 offset:2048
	ds_read_b128 v[158:161], v145 offset:3072
	v_add_u32_e32 v145, s18, v141
	ds_read_b128 v[162:165], v145
	ds_read_b128 v[166:169], v145 offset:1024
	ds_read_b128 v[170:173], v145 offset:2048
	ds_read_b128 v[174:177], v145 offset:3072
	v_lshl_add_u64 v[194:195], s[60:61], 0, v[136:137]
	s_add_i32 m0, s29, 0xc000
	ds_read_b128 v[178:181], v144
	ds_read_b128 v[182:185], v144 offset:1024
	ds_read_b128 v[186:189], v144 offset:2048
	ds_read_b128 v[190:193], v144 offset:3072
	ds_read_b128 v[202:205], v144 offset:4096
	ds_read_b128 v[206:209], v144 offset:5120
	ds_read_b128 v[210:213], v144 offset:6144
	ds_read_b128 v[214:217], v144 offset:7168
	global_load_lds_dwordx4 v[194:195], off
	v_lshl_add_u64 v[194:195], s[60:61], 0, v[138:139]
	s_add_i32 m0, s29, 0xe000
	s_nop 0
	global_load_lds_dwordx4 v[194:195], off
	s_waitcnt vmcnt(8)
	s_waitcnt lgkmcnt(0)
	s_barrier
	s_setprio 1
	s_waitcnt lgkmcnt(0)
	v_mfma_f32_16x16x32_bf16 v[114:117], v[146:149], v[178:181], v[114:117]
	v_mfma_f32_16x16x32_bf16 v[118:121], v[154:157], v[178:181], v[118:121]
	v_mfma_f32_16x16x32_bf16 v[114:117], v[150:153], v[182:185], v[114:117]
	v_mfma_f32_16x16x32_bf16 v[118:121], v[158:161], v[182:185], v[118:121]
	v_mfma_f32_16x16x32_bf16 v[98:101], v[146:149], v[186:189], v[98:101]
	v_mfma_f32_16x16x32_bf16 v[102:105], v[154:157], v[186:189], v[102:105]
	v_mfma_f32_16x16x32_bf16 v[98:101], v[150:153], v[190:193], v[98:101]
	v_mfma_f32_16x16x32_bf16 v[102:105], v[158:161], v[190:193], v[102:105]
	v_mfma_f32_16x16x32_bf16 v[82:85], v[146:149], v[202:205], v[82:85]
	v_mfma_f32_16x16x32_bf16 v[86:89], v[154:157], v[202:205], v[86:89]
	v_mfma_f32_16x16x32_bf16 v[82:85], v[150:153], v[206:209], v[82:85]
	v_mfma_f32_16x16x32_bf16 v[86:89], v[158:161], v[206:209], v[86:89]
	v_mfma_f32_16x16x32_bf16 v[66:69], v[146:149], v[210:213], v[66:69]
	v_mfma_f32_16x16x32_bf16 v[70:73], v[154:157], v[210:213], v[70:73]
	v_mfma_f32_16x16x32_bf16 v[66:69], v[150:153], v[214:217], v[66:69]
	v_mfma_f32_16x16x32_bf16 v[70:73], v[158:161], v[214:217], v[70:73]
	s_setprio 0
	s_setprio 1
	v_mfma_f32_16x16x32_bf16 v[122:125], v[162:165], v[178:181], v[122:125]
	v_mfma_f32_16x16x32_bf16 v[126:129], v[170:173], v[178:181], v[126:129]
	v_mfma_f32_16x16x32_bf16 v[122:125], v[166:169], v[182:185], v[122:125]
	v_mfma_f32_16x16x32_bf16 v[126:129], v[174:177], v[182:185], v[126:129]
	v_mfma_f32_16x16x32_bf16 v[106:109], v[162:165], v[186:189], v[106:109]
	v_mfma_f32_16x16x32_bf16 v[110:113], v[170:173], v[186:189], v[110:113]
	v_mfma_f32_16x16x32_bf16 v[106:109], v[166:169], v[190:193], v[106:109]
	v_mfma_f32_16x16x32_bf16 v[110:113], v[174:177], v[190:193], v[110:113]
	v_mfma_f32_16x16x32_bf16 v[90:93], v[162:165], v[202:205], v[90:93]
	v_mfma_f32_16x16x32_bf16 v[94:97], v[170:173], v[202:205], v[94:97]
	v_mfma_f32_16x16x32_bf16 v[90:93], v[166:169], v[206:209], v[90:93]
	v_mfma_f32_16x16x32_bf16 v[94:97], v[174:177], v[206:209], v[94:97]
	v_mfma_f32_16x16x32_bf16 v[74:77], v[162:165], v[210:213], v[74:77]
	v_mfma_f32_16x16x32_bf16 v[78:81], v[170:173], v[210:213], v[78:81]
	v_mfma_f32_16x16x32_bf16 v[74:77], v[166:169], v[214:217], v[74:77]
	v_mfma_f32_16x16x32_bf16 v[78:81], v[174:177], v[214:217], v[78:81]
	s_setprio 0
	s_barrier
	s_add_i32 s38, s39, s27
	v_lshl_add_u64 v[194:195], s[56:57], 0, v[0:1]
	s_mov_b32 m0, s38
	ds_read_b128 v[178:181], v144 offset:16384
	ds_read_b128 v[182:185], v144 offset:17408
	ds_read_b128 v[186:189], v144 offset:18432
	ds_read_b128 v[190:193], v144 offset:19456
	ds_read_b128 v[202:205], v144 offset:20480
	ds_read_b128 v[206:209], v144 offset:21504
	ds_read_b128 v[210:213], v144 offset:22528
	ds_read_b128 v[214:217], v144 offset:23552
	global_load_lds_dwordx4 v[194:195], off
	s_add_i32 m0, s38, 0x2000
	s_add_u32 s38, s56, 0x40000
	v_lshl_add_u64 v[218:219], s[56:57], 0, v[130:131]
	s_addc_u32 s39, s57, 0
	s_add_i32 s18, s18, s27
	global_load_lds_dwordx4 v[218:219], off
	v_lshl_add_u64 v[220:221], s[38:39], 0, v[0:1]
	s_mov_b32 m0, s18
	v_lshl_add_u64 v[222:223], s[64:65], 0, v[132:133]
	global_load_lds_dwordx4 v[220:221], off
	v_lshl_add_u64 v[220:221], s[38:39], 0, v[130:131]
	s_add_i32 m0, s18, 0x2000
	s_nop 0
	global_load_lds_dwordx4 v[220:221], off
	v_lshl_add_u64 v[220:221], s[64:65], 0, v[134:135]
	s_mov_b32 m0, s29
	s_nop 0
	global_load_lds_dwordx4 v[220:221], off
	s_mov_b32 m0, s33
	s_nop 0
	global_load_lds_dwordx4 v[222:223], off
	s_waitcnt vmcnt(8)
	s_waitcnt lgkmcnt(0)
	s_barrier
; #define PG8_STAGE(bufoff, gbase, voff) do { _Pragma("unroll") for (int _i = 0; _i < 2; ++_i) \
;         __builtin_amdgcn_global_load_lds((const unsigned*)((const char*)(gbase) + (voff)[_i]), (PG8_LAS unsigned*)(lds + (bufoff) + ldsw + _i * 8192), 16, 0, 0); } while (0)
; #define PG8_LDA(dst, b, h) do { _Pragma("unroll") for (int m = 0; m < 4; ++m) _Pragma("unroll") for (int k = 0; k < 2; ++k) dst[m][k] = *(const PG8_LAS bf16x8*)(lds + PG8_SA(b, h) + aoff + m * 2048 + k * 1024); } while (0)
; #define PG8_LDB(dst, b, h) do { _Pragma("unroll") for (int n = 0; n < 2; ++n) _Pragma("unroll") for (int k = 0; k < 2; ++k) dst[n][k] = *(const PG8_LAS bf16x8*)(lds + PG8_SB(b, h) + boff + n * 2048 + k * 1024); } while (0)
; #define PG8_MMA(ai, bj, At, Bt) do { __builtin_amdgcn_s_setprio(1); _Pragma("unroll") for (int m = 0; m < 4; ++m) _Pragma("unroll") for (int n = 0; n < 2; ++n) _Pragma("unroll") for (int k = 0; k < 2; ++k) \
;         acc[ai][bj][m][n] = __builtin_amdgcn_mfma_f32_16x16x32_bf16(Bt[n][k], At[m][k], acc[ai][bj][m][n], 0, 0, 0); __builtin_amdgcn_s_setprio(0); } while (0)
; #define PG8_WAIT_V(n) asm volatile("s_waitcnt vmcnt(" #n ")" ::: "memory")
; #define PG8_WAIT_L(n) asm volatile("s_waitcnt lgkmcnt(" #n ")" ::: "memory")
; #define PG8_BAR __builtin_amdgcn_s_barrier()
; #define PG8_SCHED __builtin_amdgcn_sched_barrier(0)
; template <class Epi, class Sched, bool ALIGN_EPI = false, bool SP2 = false>
; __device__ __forceinline__ void gemm_phase(PG8_LAS unsigned char* lds, const Gemm g, const Sched& S, const Epi& E) {
;     ...
;             PG8_WAIT_V(8); PG8_WAIT_L(0); PG8_BAR; PG8_MMA(1, 0, At, B0); PG8_MMA(1, 1, At, B1); PG8_BAR; PG8_SCHED;
;             PG8_LDB(B0, 1, 0); PG8_LDB(B1, 1, 1); PG8_SCHED; PG8_LDA(At, 1, 0); PG8_STAGE(PG8_SA(0, 1), a2 + hstep, voffA);
;             PG8_WAIT_V(8); PG8_WAIT_L(0); PG8_BAR; PG8_MMA(0, 0, At, B0); PG8_MMA(0, 1, At, B1); PG8_BAR; PG8_SCHED;
	s_setprio 1
	s_waitcnt lgkmcnt(0)
	v_mfma_f32_16x16x32_bf16 v[50:53], v[146:149], v[178:181], v[50:53]
	v_mfma_f32_16x16x32_bf16 v[54:57], v[154:157], v[178:181], v[54:57]
	v_mfma_f32_16x16x32_bf16 v[50:53], v[150:153], v[182:185], v[50:53]
	v_mfma_f32_16x16x32_bf16 v[54:57], v[158:161], v[182:185], v[54:57]
	v_mfma_f32_16x16x32_bf16 v[34:37], v[146:149], v[186:189], v[34:37]
	v_mfma_f32_16x16x32_bf16 v[38:41], v[154:157], v[186:189], v[38:41]
	v_mfma_f32_16x16x32_bf16 v[34:37], v[150:153], v[190:193], v[34:37]
	v_mfma_f32_16x16x32_bf16 v[38:41], v[158:161], v[190:193], v[38:41]
	v_mfma_f32_16x16x32_bf16 v[18:21], v[146:149], v[202:205], v[18:21]
	v_mfma_f32_16x16x32_bf16 v[22:25], v[154:157], v[202:205], v[22:25]
	v_mfma_f32_16x16x32_bf16 v[18:21], v[150:153], v[206:209], v[18:21]
	v_mfma_f32_16x16x32_bf16 v[22:25], v[158:161], v[206:209], v[22:25]
	v_mfma_f32_16x16x32_bf16 v[2:5], v[146:149], v[210:213], v[2:5]
	v_mfma_f32_16x16x32_bf16 v[6:9], v[154:157], v[210:213], v[6:9]
	v_mfma_f32_16x16x32_bf16 v[2:5], v[150:153], v[214:217], v[2:5]
	v_mfma_f32_16x16x32_bf16 v[6:9], v[158:161], v[214:217], v[6:9]
	s_setprio 0
	s_setprio 1
	v_mfma_f32_16x16x32_bf16 v[58:61], v[162:165], v[178:181], v[58:61]
	v_mfma_f32_16x16x32_bf16 v[62:65], v[170:173], v[178:181], v[62:65]
	v_mfma_f32_16x16x32_bf16 v[58:61], v[166:169], v[182:185], v[58:61]
	v_mfma_f32_16x16x32_bf16 v[62:65], v[174:177], v[182:185], v[62:65]
	v_mfma_f32_16x16x32_bf16 v[42:45], v[162:165], v[186:189], v[42:45]
	v_mfma_f32_16x16x32_bf16 v[46:49], v[170:173], v[186:189], v[46:49]
	v_mfma_f32_16x16x32_bf16 v[42:45], v[166:169], v[190:193], v[42:45]
	v_mfma_f32_16x16x32_bf16 v[46:49], v[174:177], v[190:193], v[46:49]
	v_mfma_f32_16x16x32_bf16 v[26:29], v[162:165], v[202:205], v[26:29]
	v_mfma_f32_16x16x32_bf16 v[30:33], v[170:173], v[202:205], v[30:33]
	v_mfma_f32_16x16x32_bf16 v[26:29], v[166:169], v[206:209], v[26:29]
	v_mfma_f32_16x16x32_bf16 v[30:33], v[174:177], v[206:209], v[30:33]
	v_mfma_f32_16x16x32_bf16 v[10:13], v[162:165], v[210:213], v[10:13]
	v_mfma_f32_16x16x32_bf16 v[14:17], v[170:173], v[210:213], v[14:17]
	v_mfma_f32_16x16x32_bf16 v[10:13], v[166:169], v[214:217], v[10:13]
	v_mfma_f32_16x16x32_bf16 v[14:17], v[174:177], v[214:217], v[14:17]
	s_setprio 0
	s_barrier
	s_add_i32 s18, 0, 0x18000
	v_add_u32_e32 v145, s18, v141
	s_add_i32 s83, 0, 0x1c000
	ds_read_b128 v[146:149], v145
	ds_read_b128 v[150:153], v145 offset:1024
	ds_read_b128 v[154:157], v145 offset:2048
	ds_read_b128 v[158:161], v145 offset:3072
	v_add_u32_e32 v145, s83, v141
	ds_read_b128 v[162:165], v145
	ds_read_b128 v[166:169], v145 offset:1024
	ds_read_b128 v[170:173], v145 offset:2048
	ds_read_b128 v[174:177], v145 offset:3072
	s_add_u32 s38, s64, 0x40000
	s_addc_u32 s39, s65, 0
	s_mov_b32 m0, s58
	v_lshl_add_u64 v[224:225], s[38:39], 0, v[134:135]
	ds_read_b128 v[178:181], v144 offset:32768
	ds_read_b128 v[182:185], v144 offset:33792
	ds_read_b128 v[186:189], v144 offset:34816
	ds_read_b128 v[190:193], v144 offset:35840
	ds_read_b128 v[202:205], v144 offset:36864
	ds_read_b128 v[206:209], v144 offset:37888
	ds_read_b128 v[210:213], v144 offset:38912
	ds_read_b128 v[214:217], v144 offset:39936
	global_load_lds_dwordx4 v[224:225], off
	v_lshl_add_u64 v[224:225], s[38:39], 0, v[132:133]
	s_mov_b32 m0, s69
	s_nop 0
	global_load_lds_dwordx4 v[224:225], off
	s_waitcnt vmcnt(8)
	s_waitcnt lgkmcnt(0)
	s_barrier
	s_setprio 1
	s_waitcnt lgkmcnt(0)
	v_mfma_f32_16x16x32_bf16 v[114:117], v[146:149], v[178:181], v[114:117]
	v_mfma_f32_16x16x32_bf16 v[118:121], v[154:157], v[178:181], v[118:121]
	v_mfma_f32_16x16x32_bf16 v[114:117], v[150:153], v[182:185], v[114:117]
	v_mfma_f32_16x16x32_bf16 v[118:121], v[158:161], v[182:185], v[118:121]
	v_mfma_f32_16x16x32_bf16 v[98:101], v[146:149], v[186:189], v[98:101]
	v_mfma_f32_16x16x32_bf16 v[102:105], v[154:157], v[186:189], v[102:105]
	v_mfma_f32_16x16x32_bf16 v[98:101], v[150:153], v[190:193], v[98:101]
	v_mfma_f32_16x16x32_bf16 v[102:105], v[158:161], v[190:193], v[102:105]
	v_mfma_f32_16x16x32_bf16 v[82:85], v[146:149], v[202:205], v[82:85]
	v_mfma_f32_16x16x32_bf16 v[86:89], v[154:157], v[202:205], v[86:89]
	v_mfma_f32_16x16x32_bf16 v[82:85], v[150:153], v[206:209], v[82:85]
	v_mfma_f32_16x16x32_bf16 v[86:89], v[158:161], v[206:209], v[86:89]
	v_mfma_f32_16x16x32_bf16 v[66:69], v[146:149], v[210:213], v[66:69]
	v_mfma_f32_16x16x32_bf16 v[70:73], v[154:157], v[210:213], v[70:73]
	v_mfma_f32_16x16x32_bf16 v[66:69], v[150:153], v[214:217], v[66:69]
	v_mfma_f32_16x16x32_bf16 v[70:73], v[158:161], v[214:217], v[70:73]
	s_setprio 0
	s_setprio 1
	v_mfma_f32_16x16x32_bf16 v[122:125], v[162:165], v[178:181], v[122:125]
	v_mfma_f32_16x16x32_bf16 v[126:129], v[170:173], v[178:181], v[126:129]
	v_mfma_f32_16x16x32_bf16 v[122:125], v[166:169], v[182:185], v[122:125]
	v_mfma_f32_16x16x32_bf16 v[126:129], v[174:177], v[182:185], v[126:129]
	v_mfma_f32_16x16x32_bf16 v[106:109], v[162:165], v[186:189], v[106:109]
	v_mfma_f32_16x16x32_bf16 v[110:113], v[170:173], v[186:189], v[110:113]
	v_mfma_f32_16x16x32_bf16 v[106:109], v[166:169], v[190:193], v[106:109]
	v_mfma_f32_16x16x32_bf16 v[110:113], v[174:177], v[190:193], v[110:113]
	v_mfma_f32_16x16x32_bf16 v[90:93], v[162:165], v[202:205], v[90:93]
	v_mfma_f32_16x16x32_bf16 v[94:97], v[170:173], v[202:205], v[94:97]
	v_mfma_f32_16x16x32_bf16 v[90:93], v[166:169], v[206:209], v[90:93]
	v_mfma_f32_16x16x32_bf16 v[94:97], v[174:177], v[206:209], v[94:97]
	v_mfma_f32_16x16x32_bf16 v[74:77], v[162:165], v[210:213], v[74:77]
	v_mfma_f32_16x16x32_bf16 v[78:81], v[170:173], v[210:213], v[78:81]
	v_mfma_f32_16x16x32_bf16 v[74:77], v[166:169], v[214:217], v[74:77]
	v_mfma_f32_16x16x32_bf16 v[78:81], v[174:177], v[214:217], v[78:81]
	s_setprio 0
	s_barrier
; #define PG8_STAGE(bufoff, gbase, voff) do { _Pragma("unroll") for (int _i = 0; _i < 2; ++_i) \
;         __builtin_amdgcn_global_load_lds((const unsigned*)((const char*)(gbase) + (voff)[_i]), (PG8_LAS unsigned*)(lds + (bufoff) + ldsw + _i * 8192), 16, 0, 0); } while (0)
; #define PG8_LDA(dst, b, h) do { _Pragma("unroll") for (int m = 0; m < 4; ++m) _Pragma("unroll") for (int k = 0; k < 2; ++k) dst[m][k] = *(const PG8_LAS bf16x8*)(lds + PG8_SA(b, h) + aoff + m * 2048 + k * 1024); } while (0)
; #define PG8_MMA(ai, bj, At, Bt) do { __builtin_amdgcn_s_setprio(1); _Pragma("unroll") for (int m = 0; m < 4; ++m) _Pragma("unroll") for (int n = 0; n < 2; ++n) _Pragma("unroll") for (int k = 0; k < 2; ++k) \
;         acc[ai][bj][m][n] = __builtin_amdgcn_mfma_f32_16x16x32_bf16(Bt[n][k], At[m][k], acc[ai][bj][m][n], 0, 0, 0); __builtin_amdgcn_s_setprio(0); } while (0)
; #define PG8_WAIT_V(n) asm volatile("s_waitcnt vmcnt(" #n ")" ::: "memory")
; #define PG8_WAIT_L(n) asm volatile("s_waitcnt lgkmcnt(" #n ")" ::: "memory")
; #define PG8_BAR __builtin_amdgcn_s_barrier()
; #define PG8_SCHED __builtin_amdgcn_sched_barrier(0)
; template <class Epi, class Sched, bool ALIGN_EPI = false, bool SP2 = false>
; __device__ __forceinline__ void gemm_phase(PG8_LAS unsigned char* lds, const Gemm g, const Sched& S, const Epi& E) {
;     ...
;             PG8_LDA(At, 1, 1); PG8_STAGE(PG8_SB(1, 0), b3, voffB); PG8_STAGE(PG8_SB(1, 1), b3 + hstep, voffB); PG8_STAGE(PG8_SA(1, 0), a3, voffA);
;             PG8_WAIT_V(8); PG8_WAIT_L(0); PG8_BAR; PG8_MMA(1, 0, At, B0); PG8_MMA(1, 1, At, B1); PG8_BAR; PG8_SCHED;
	s_add_i32 s18, s18, s27
	v_lshl_add_u64 v[194:195], v[194:195], 0, s[30:31]
	s_mov_b32 m0, s18
	ds_read_b128 v[178:181], v144 offset:49152
	ds_read_b128 v[182:185], v144 offset:50176
	ds_read_b128 v[186:189], v144 offset:51200
	ds_read_b128 v[190:193], v144 offset:52224
	ds_read_b128 v[202:205], v144 offset:53248
	ds_read_b128 v[206:209], v144 offset:54272
	ds_read_b128 v[210:213], v144 offset:55296
	ds_read_b128 v[214:217], v144 offset:56320
	global_load_lds_dwordx4 v[194:195], off
	s_add_i32 m0, s18, 0x2000
	s_add_u32 s38, s56, 0x40080
	v_lshl_add_u64 v[194:195], v[218:219], 0, s[30:31]
	s_addc_u32 s39, s57, 0
	s_add_i32 s18, s83, s27
	global_load_lds_dwordx4 v[194:195], off
	v_lshl_add_u64 v[194:195], s[38:39], 0, v[0:1]
	s_mov_b32 m0, s18
	s_nop 0
	global_load_lds_dwordx4 v[194:195], off
	v_lshl_add_u64 v[194:195], s[38:39], 0, v[130:131]
	s_add_i32 m0, s18, 0x2000
	s_nop 0
	global_load_lds_dwordx4 v[194:195], off
	v_lshl_add_u64 v[194:195], v[220:221], 0, s[30:31]
	s_mov_b32 m0, s71
	s_nop 0
	global_load_lds_dwordx4 v[194:195], off
	v_lshl_add_u64 v[194:195], v[222:223], 0, s[30:31]
	s_mov_b32 m0, s72
	s_nop 0
	global_load_lds_dwordx4 v[194:195], off
	s_waitcnt vmcnt(8)
	s_waitcnt lgkmcnt(0)
	s_barrier
	s_setprio 1
	s_waitcnt lgkmcnt(0)
	v_mfma_f32_16x16x32_bf16 v[50:53], v[146:149], v[178:181], v[50:53]
	v_mfma_f32_16x16x32_bf16 v[54:57], v[154:157], v[178:181], v[54:57]
	v_mfma_f32_16x16x32_bf16 v[50:53], v[150:153], v[182:185], v[50:53]
	v_mfma_f32_16x16x32_bf16 v[54:57], v[158:161], v[182:185], v[54:57]
	v_mfma_f32_16x16x32_bf16 v[34:37], v[146:149], v[186:189], v[34:37]
	v_mfma_f32_16x16x32_bf16 v[38:41], v[154:157], v[186:189], v[38:41]
	v_mfma_f32_16x16x32_bf16 v[34:37], v[150:153], v[190:193], v[34:37]
	v_mfma_f32_16x16x32_bf16 v[38:41], v[158:161], v[190:193], v[38:41]
	v_mfma_f32_16x16x32_bf16 v[18:21], v[146:149], v[202:205], v[18:21]
	v_mfma_f32_16x16x32_bf16 v[22:25], v[154:157], v[202:205], v[22:25]
	v_mfma_f32_16x16x32_bf16 v[18:21], v[150:153], v[206:209], v[18:21]
	v_mfma_f32_16x16x32_bf16 v[22:25], v[158:161], v[206:209], v[22:25]
	v_mfma_f32_16x16x32_bf16 v[2:5], v[146:149], v[210:213], v[2:5]
	v_mfma_f32_16x16x32_bf16 v[6:9], v[154:157], v[210:213], v[6:9]
	v_mfma_f32_16x16x32_bf16 v[2:5], v[150:153], v[214:217], v[2:5]
	v_mfma_f32_16x16x32_bf16 v[6:9], v[158:161], v[214:217], v[6:9]
	s_setprio 0
	s_setprio 1
	v_mfma_f32_16x16x32_bf16 v[58:61], v[162:165], v[178:181], v[58:61]
	v_mfma_f32_16x16x32_bf16 v[62:65], v[170:173], v[178:181], v[62:65]
	v_mfma_f32_16x16x32_bf16 v[58:61], v[166:169], v[182:185], v[58:61]
	v_mfma_f32_16x16x32_bf16 v[62:65], v[174:177], v[182:185], v[62:65]
	v_mfma_f32_16x16x32_bf16 v[42:45], v[162:165], v[186:189], v[42:45]
	v_mfma_f32_16x16x32_bf16 v[46:49], v[170:173], v[186:189], v[46:49]
	v_mfma_f32_16x16x32_bf16 v[42:45], v[166:169], v[190:193], v[42:45]
	v_mfma_f32_16x16x32_bf16 v[46:49], v[174:177], v[190:193], v[46:49]
	v_mfma_f32_16x16x32_bf16 v[26:29], v[162:165], v[202:205], v[26:29]
	v_mfma_f32_16x16x32_bf16 v[30:33], v[170:173], v[202:205], v[30:33]
	v_mfma_f32_16x16x32_bf16 v[26:29], v[166:169], v[206:209], v[26:29]
	v_mfma_f32_16x16x32_bf16 v[30:33], v[174:177], v[206:209], v[30:33]
	v_mfma_f32_16x16x32_bf16 v[10:13], v[162:165], v[210:213], v[10:13]
	v_mfma_f32_16x16x32_bf16 v[14:17], v[170:173], v[210:213], v[14:17]
	v_mfma_f32_16x16x32_bf16 v[10:13], v[166:169], v[214:217], v[10:13]
	v_mfma_f32_16x16x32_bf16 v[14:17], v[174:177], v[214:217], v[14:17]
	s_setprio 0
	s_barrier
	s_add_i32 s82, s82, 2
	s_add_u32 s60, s60, 0x100
	s_addc_u32 s61, s61, 0
	s_add_u32 s80, s80, 0x100
	s_addc_u32 s81, s81, 0
	s_cmp_gt_u32 s82, 13
	s_cbranch_scc0 .LBB0_220
	s_and_b64 vcc, exec, s[44:45]
	s_cbranch_vccz .LBB0_223
	s_barrier

; #define PG8_STAGE(bufoff, gbase, voff) do { _Pragma("unroll") for (int _i = 0; _i < 2; ++_i) \
;         __builtin_amdgcn_global_load_lds((const unsigned*)((const char*)(gbase) + (voff)[_i]), (PG8_LAS unsigned*)(lds + (bufoff) + ldsw + _i * 8192), 16, 0, 0); } while (0)
; #define PG8_LDA(dst, b, h) do { _Pragma("unroll") for (int m = 0; m < 4; ++m) _Pragma("unroll") for (int k = 0; k < 2; ++k) dst[m][k] = *(const PG8_LAS bf16x8*)(lds + PG8_SA(b, h) + aoff + m * 2048 + k * 1024); } while (0)
; #define PG8_LDB(dst, b, h) do { _Pragma("unroll") for (int n = 0; n < 2; ++n) _Pragma("unroll") for (int k = 0; k < 2; ++k) dst[n][k] = *(const PG8_LAS bf16x8*)(lds + PG8_SB(b, h) + boff + n * 2048 + k * 1024); } while (0)
; #define PG8_MMA(ai, bj, At, Bt) do { __builtin_amdgcn_s_setprio(1); _Pragma("unroll") for (int m = 0; m < 4; ++m) _Pragma("unroll") for (int n = 0; n < 2; ++n) _Pragma("unroll") for (int k = 0; k < 2; ++k) \
;         acc[ai][bj][m][n] = __builtin_amdgcn_mfma_f32_16x16x32_bf16(Bt[n][k], At[m][k], acc[ai][bj][m][n], 0, 0, 0); __builtin_amdgcn_s_setprio(0); } while (0)
; #define PG8_WAIT_V(n) asm volatile("s_waitcnt vmcnt(" #n ")" ::: "memory")
; #define PG8_WAIT_L(n) asm volatile("s_waitcnt lgkmcnt(" #n ")" ::: "memory")
; #define PG8_BAR __builtin_amdgcn_s_barrier()
; #define PG8_SCHED __builtin_amdgcn_sched_barrier(0)
; template <class Epi, class Sched, bool ALIGN_EPI = false, bool SP2 = false>
; __device__ __forceinline__ void gemm_phase(PG8_LAS unsigned char* lds, const Gemm g, const Sched& S, const Epi& E) {
;     ...
;             const bool last = (t == nt - 2);
;             const char* a1 = cA + (size_t)(t + 1) * kstep;
;             const char* a2 = last ? nA : cA + (size_t)(t + 2) * kstep; const char* b2 = last ? nB : cB + (size_t)(t + 2) * kstep;
;             const char* a3 = a2 + kstep; const char* b3 = b2 + kstep;
;             if (last && has_next) S.a_ready(nxt);
;             if constexpr (SP2) {
;             PG8_LDB(B0, 0, 0); PG8_LDB(B1, 0, 1); PG8_SCHED; PG8_LDA(At, 0, 0); PG8_STAGE(PG8_SA(1, 1), a1 + hstep, voffA);
;             PG8_WAIT_V(8); PG8_WAIT_L(0); PG8_BAR; PG8_MMA(0, 0, At, B0); PG8_MMA(0, 1, At, B1); PG8_BAR; PG8_SCHED;
;             PG8_LDA(At, 0, 1); PG8_STAGE(PG8_SB(0, 0), b2, voffB); PG8_STAGE(PG8_SB(0, 1), b2 + hstep, voffB); PG8_STAGE(PG8_SA(0, 0), a2, voffA);
.LBB0_274:
	s_add_i32 vcc_lo, s46, 2
	s_add_u32 s38, s48, 0x80
	s_addc_u32 s39, s49, 0
	s_add_i32 vcc_hi, 0, 0x10000
	s_cmp_eq_u32 s99, s46
	s_cselect_b32 s47, s81, s39
	s_cselect_b32 s46, s80, s38
	s_cselect_b32 s39, s83, s51
	s_cselect_b32 s38, s82, s50
	s_add_i32 s18, 0, 0x14000
	v_add_u32_e32 v142, vcc_hi, v245
	v_add_u32_e32 v158, s18, v245
	ds_read_b128 v[110:113], v142
	ds_read_b128 v[118:121], v142 offset:1024
	ds_read_b128 v[138:141], v142 offset:2048
	ds_read_b128 v[142:145], v142 offset:3072
	ds_read_b128 v[146:149], v158
	ds_read_b128 v[150:153], v158 offset:1024
	ds_read_b128 v[154:157], v158 offset:2048
	ds_read_b128 v[158:161], v158 offset:3072
	v_lshl_add_u64 v[210:211], s[48:49], 0, v[206:207]
	s_add_i32 m0, s92, 0xc000
	ds_read_b128 v[162:165], v247
	ds_read_b128 v[166:169], v247 offset:1024
	ds_read_b128 v[170:173], v247 offset:2048
	ds_read_b128 v[174:177], v247 offset:3072
	ds_read_b128 v[178:181], v247 offset:4096
	ds_read_b128 v[182:185], v247 offset:5120
	ds_read_b128 v[186:189], v247 offset:6144
	ds_read_b128 v[190:193], v247 offset:7168
	global_load_lds_dwordx4 v[210:211], off
	v_lshl_add_u64 v[210:211], s[48:49], 0, v[208:209]
	s_add_i32 m0, s92, 0xe000
	s_nop 0
	global_load_lds_dwordx4 v[210:211], off
	s_waitcnt vmcnt(8)
	s_waitcnt lgkmcnt(0)
	s_barrier
	s_setprio 1
	s_waitcnt lgkmcnt(0)
	v_mfma_f32_16x16x32_bf16 v[130:133], v[110:113], v[162:165], v[130:133]
	v_mfma_f32_16x16x32_bf16 v[134:137], v[138:141], v[162:165], v[134:137]
	v_mfma_f32_16x16x32_bf16 v[130:133], v[118:121], v[166:169], v[130:133]
	v_mfma_f32_16x16x32_bf16 v[134:137], v[142:145], v[166:169], v[134:137]
	v_mfma_f32_16x16x32_bf16 v[114:117], v[110:113], v[170:173], v[114:117]
	v_mfma_f32_16x16x32_bf16 v[106:109], v[138:141], v[170:173], v[106:109]
	v_mfma_f32_16x16x32_bf16 v[114:117], v[118:121], v[174:177], v[114:117]
	v_mfma_f32_16x16x32_bf16 v[106:109], v[142:145], v[174:177], v[106:109]
	v_mfma_f32_16x16x32_bf16 v[94:97], v[110:113], v[178:181], v[94:97]
	v_mfma_f32_16x16x32_bf16 v[90:93], v[138:141], v[178:181], v[90:93]
	v_mfma_f32_16x16x32_bf16 v[94:97], v[118:121], v[182:185], v[94:97]
	v_mfma_f32_16x16x32_bf16 v[90:93], v[142:145], v[182:185], v[90:93]
	v_mfma_f32_16x16x32_bf16 v[78:81], v[110:113], v[186:189], v[78:81]
	v_mfma_f32_16x16x32_bf16 v[74:77], v[138:141], v[186:189], v[74:77]
	v_mfma_f32_16x16x32_bf16 v[78:81], v[118:121], v[190:193], v[78:81]
	v_mfma_f32_16x16x32_bf16 v[74:77], v[142:145], v[190:193], v[74:77]
	s_setprio 0
	s_setprio 1
	v_mfma_f32_16x16x32_bf16 v[126:129], v[146:149], v[162:165], v[126:129]
	v_mfma_f32_16x16x32_bf16 v[122:125], v[154:157], v[162:165], v[122:125]
	v_mfma_f32_16x16x32_bf16 v[126:129], v[150:153], v[166:169], v[126:129]
	v_mfma_f32_16x16x32_bf16 v[122:125], v[158:161], v[166:169], v[122:125]
	v_mfma_f32_16x16x32_bf16 v[102:105], v[146:149], v[170:173], v[102:105]
	v_mfma_f32_16x16x32_bf16 v[98:101], v[154:157], v[170:173], v[98:101]
	v_mfma_f32_16x16x32_bf16 v[102:105], v[150:153], v[174:177], v[102:105]
	v_mfma_f32_16x16x32_bf16 v[98:101], v[158:161], v[174:177], v[98:101]
	v_mfma_f32_16x16x32_bf16 v[86:89], v[146:149], v[178:181], v[86:89]
	v_mfma_f32_16x16x32_bf16 v[82:85], v[154:157], v[178:181], v[82:85]
	v_mfma_f32_16x16x32_bf16 v[86:89], v[150:153], v[182:185], v[86:89]
	v_mfma_f32_16x16x32_bf16 v[82:85], v[158:161], v[182:185], v[82:85]
	v_mfma_f32_16x16x32_bf16 v[70:73], v[146:149], v[186:189], v[70:73]
	v_mfma_f32_16x16x32_bf16 v[66:69], v[154:157], v[186:189], v[66:69]
	v_mfma_f32_16x16x32_bf16 v[70:73], v[150:153], v[190:193], v[70:73]
	v_mfma_f32_16x16x32_bf16 v[66:69], v[158:161], v[190:193], v[66:69]
	s_setprio 0
	s_barrier
	s_add_i32 vcc_hi, vcc_hi, s6
	v_lshl_add_u64 v[210:211], s[38:39], 0, v[0:1]
	s_mov_b32 m0, vcc_hi
	ds_read_b128 v[162:165], v247 offset:16384
	ds_read_b128 v[166:169], v247 offset:17408
	ds_read_b128 v[170:173], v247 offset:18432
	ds_read_b128 v[174:177], v247 offset:19456
	ds_read_b128 v[178:181], v247 offset:20480
	ds_read_b128 v[182:185], v247 offset:21504
	ds_read_b128 v[186:189], v247 offset:22528
	ds_read_b128 v[190:193], v247 offset:23552
	global_load_lds_dwordx4 v[210:211], off
	s_add_i32 m0, vcc_hi, 0x2000
	v_lshl_add_u64 v[212:213], s[38:39], 0, v[204:205]
	s_add_u32 s38, s38, s58
	s_addc_u32 s39, s39, 0
	s_add_i32 s18, s18, s6
	global_load_lds_dwordx4 v[212:213], off
	v_lshl_add_u64 v[214:215], s[38:39], 0, v[0:1]
	s_mov_b32 m0, s18
	v_lshl_add_u64 v[216:217], s[38:39], 0, v[204:205]
	global_load_lds_dwordx4 v[214:215], off
	s_add_i32 m0, s18, 0x2000
	v_lshl_add_u64 v[218:219], s[46:47], 0, v[194:195]
	global_load_lds_dwordx4 v[216:217], off
	s_mov_b32 m0, s92
	v_lshl_add_u64 v[220:221], s[46:47], 0, v[202:203]
	global_load_lds_dwordx4 v[218:219], off
	s_mov_b32 m0, s93
	s_nop 0
	global_load_lds_dwordx4 v[220:221], off
	s_waitcnt vmcnt(8)
	s_waitcnt lgkmcnt(0)
	s_barrier
; #define PG8_STAGE(bufoff, gbase, voff) do { _Pragma("unroll") for (int _i = 0; _i < 2; ++_i) \
;         __builtin_amdgcn_global_load_lds((const unsigned*)((const char*)(gbase) + (voff)[_i]), (PG8_LAS unsigned*)(lds + (bufoff) + ldsw + _i * 8192), 16, 0, 0); } while (0)
; #define PG8_LDA(dst, b, h) do { _Pragma("unroll") for (int m = 0; m < 4; ++m) _Pragma("unroll") for (int k = 0; k < 2; ++k) dst[m][k] = *(const PG8_LAS bf16x8*)(lds + PG8_SA(b, h) + aoff + m * 2048 + k * 1024); } while (0)
; #define PG8_LDB(dst, b, h) do { _Pragma("unroll") for (int n = 0; n < 2; ++n) _Pragma("unroll") for (int k = 0; k < 2; ++k) dst[n][k] = *(const PG8_LAS bf16x8*)(lds + PG8_SB(b, h) + boff + n * 2048 + k * 1024); } while (0)
; #define PG8_MMA(ai, bj, At, Bt) do { __builtin_amdgcn_s_setprio(1); _Pragma("unroll") for (int m = 0; m < 4; ++m) _Pragma("unroll") for (int n = 0; n < 2; ++n) _Pragma("unroll") for (int k = 0; k < 2; ++k) \
;         acc[ai][bj][m][n] = __builtin_amdgcn_mfma_f32_16x16x32_bf16(Bt[n][k], At[m][k], acc[ai][bj][m][n], 0, 0, 0); __builtin_amdgcn_s_setprio(0); } while (0)
; #define PG8_WAIT_V(n) asm volatile("s_waitcnt vmcnt(" #n ")" ::: "memory")
; #define PG8_WAIT_L(n) asm volatile("s_waitcnt lgkmcnt(" #n ")" ::: "memory")
; #define PG8_BAR __builtin_amdgcn_s_barrier()
; #define PG8_SCHED __builtin_amdgcn_sched_barrier(0)
; template <class Epi, class Sched, bool ALIGN_EPI = false, bool SP2 = false>
; __device__ __forceinline__ void gemm_phase(PG8_LAS unsigned char* lds, const Gemm g, const Sched& S, const Epi& E) {
;     ...
;             PG8_WAIT_V(8); PG8_WAIT_L(0); PG8_BAR; PG8_MMA(1, 0, At, B0); PG8_MMA(1, 1, At, B1); PG8_BAR; PG8_SCHED;
;             PG8_LDB(B0, 1, 0); PG8_LDB(B1, 1, 1); PG8_SCHED; PG8_LDA(At, 1, 0); PG8_STAGE(PG8_SA(0, 1), a2 + hstep, voffA);
;             PG8_WAIT_V(8); PG8_WAIT_L(0); PG8_BAR; PG8_MMA(0, 0, At, B0); PG8_MMA(0, 1, At, B1); PG8_BAR; PG8_SCHED;
	s_setprio 1
	s_waitcnt lgkmcnt(0)
	v_mfma_f32_16x16x32_bf16 v[62:65], v[110:113], v[162:165], v[62:65]
	v_mfma_f32_16x16x32_bf16 v[58:61], v[138:141], v[162:165], v[58:61]
	v_mfma_f32_16x16x32_bf16 v[62:65], v[118:121], v[166:169], v[62:65]
	v_mfma_f32_16x16x32_bf16 v[58:61], v[142:145], v[166:169], v[58:61]
	v_mfma_f32_16x16x32_bf16 v[46:49], v[110:113], v[170:173], v[46:49]
	v_mfma_f32_16x16x32_bf16 v[42:45], v[138:141], v[170:173], v[42:45]
	v_mfma_f32_16x16x32_bf16 v[46:49], v[118:121], v[174:177], v[46:49]
	v_mfma_f32_16x16x32_bf16 v[42:45], v[142:145], v[174:177], v[42:45]
	v_mfma_f32_16x16x32_bf16 v[30:33], v[110:113], v[178:181], v[30:33]
	v_mfma_f32_16x16x32_bf16 v[26:29], v[138:141], v[178:181], v[26:29]
	v_mfma_f32_16x16x32_bf16 v[30:33], v[118:121], v[182:185], v[30:33]
	v_mfma_f32_16x16x32_bf16 v[26:29], v[142:145], v[182:185], v[26:29]
	v_mfma_f32_16x16x32_bf16 v[14:17], v[110:113], v[186:189], v[14:17]
	v_mfma_f32_16x16x32_bf16 v[10:13], v[138:141], v[186:189], v[10:13]
	v_mfma_f32_16x16x32_bf16 v[14:17], v[118:121], v[190:193], v[14:17]
	v_mfma_f32_16x16x32_bf16 v[10:13], v[142:145], v[190:193], v[10:13]
	s_setprio 0
	s_setprio 1
	v_mfma_f32_16x16x32_bf16 v[54:57], v[146:149], v[162:165], v[54:57]
	v_mfma_f32_16x16x32_bf16 v[50:53], v[154:157], v[162:165], v[50:53]
	v_mfma_f32_16x16x32_bf16 v[54:57], v[150:153], v[166:169], v[54:57]
	v_mfma_f32_16x16x32_bf16 v[50:53], v[158:161], v[166:169], v[50:53]
	v_mfma_f32_16x16x32_bf16 v[38:41], v[146:149], v[170:173], v[38:41]
	v_mfma_f32_16x16x32_bf16 v[34:37], v[154:157], v[170:173], v[34:37]
	v_mfma_f32_16x16x32_bf16 v[38:41], v[150:153], v[174:177], v[38:41]
	v_mfma_f32_16x16x32_bf16 v[34:37], v[158:161], v[174:177], v[34:37]
	v_mfma_f32_16x16x32_bf16 v[22:25], v[146:149], v[178:181], v[22:25]
	v_mfma_f32_16x16x32_bf16 v[18:21], v[154:157], v[178:181], v[18:21]
	v_mfma_f32_16x16x32_bf16 v[22:25], v[150:153], v[182:185], v[22:25]
	v_mfma_f32_16x16x32_bf16 v[18:21], v[158:161], v[182:185], v[18:21]
	v_mfma_f32_16x16x32_bf16 v[6:9], v[146:149], v[186:189], v[6:9]
	v_mfma_f32_16x16x32_bf16 v[2:5], v[154:157], v[186:189], v[2:5]
	v_mfma_f32_16x16x32_bf16 v[6:9], v[150:153], v[190:193], v[6:9]
	v_mfma_f32_16x16x32_bf16 v[2:5], v[158:161], v[190:193], v[2:5]
	s_setprio 0
	s_barrier
	s_add_i32 s18, 0, 0x18000
	s_add_i32 vcc_hi, 0, 0x1c000
	v_add_u32_e32 v142, s18, v245
	v_add_u32_e32 v158, vcc_hi, v245
	ds_read_b128 v[110:113], v142
	ds_read_b128 v[118:121], v142 offset:1024
	ds_read_b128 v[138:141], v142 offset:2048
	ds_read_b128 v[142:145], v142 offset:3072
	ds_read_b128 v[146:149], v158
	ds_read_b128 v[150:153], v158 offset:1024
	ds_read_b128 v[154:157], v158 offset:2048
	ds_read_b128 v[158:161], v158 offset:3072
	s_add_u32 s38, s46, s58
	s_addc_u32 s39, s47, 0
	s_mov_b32 m0, s94
	v_lshl_add_u64 v[222:223], s[38:39], 0, v[194:195]
	ds_read_b128 v[162:165], v247 offset:32768
	ds_read_b128 v[166:169], v247 offset:33792
	ds_read_b128 v[170:173], v247 offset:34816
	ds_read_b128 v[174:177], v247 offset:35840
	ds_read_b128 v[178:181], v247 offset:36864
	ds_read_b128 v[182:185], v247 offset:37888
	ds_read_b128 v[186:189], v247 offset:38912
	ds_read_b128 v[190:193], v247 offset:39936
	global_load_lds_dwordx4 v[222:223], off
	v_lshl_add_u64 v[222:223], s[38:39], 0, v[202:203]
	s_mov_b32 m0, s95
	s_nop 0
	global_load_lds_dwordx4 v[222:223], off
	s_waitcnt vmcnt(8)
	s_waitcnt lgkmcnt(0)
	s_barrier
	s_setprio 1
	s_waitcnt lgkmcnt(0)
	v_mfma_f32_16x16x32_bf16 v[130:133], v[110:113], v[162:165], v[130:133]
	v_mfma_f32_16x16x32_bf16 v[134:137], v[138:141], v[162:165], v[134:137]
	v_mfma_f32_16x16x32_bf16 v[130:133], v[118:121], v[166:169], v[130:133]
	v_mfma_f32_16x16x32_bf16 v[134:137], v[142:145], v[166:169], v[134:137]
	v_mfma_f32_16x16x32_bf16 v[114:117], v[110:113], v[170:173], v[114:117]
	v_mfma_f32_16x16x32_bf16 v[106:109], v[138:141], v[170:173], v[106:109]
	v_mfma_f32_16x16x32_bf16 v[114:117], v[118:121], v[174:177], v[114:117]
	v_mfma_f32_16x16x32_bf16 v[106:109], v[142:145], v[174:177], v[106:109]
	v_mfma_f32_16x16x32_bf16 v[94:97], v[110:113], v[178:181], v[94:97]
	v_mfma_f32_16x16x32_bf16 v[90:93], v[138:141], v[178:181], v[90:93]
	v_mfma_f32_16x16x32_bf16 v[94:97], v[118:121], v[182:185], v[94:97]
	v_mfma_f32_16x16x32_bf16 v[90:93], v[142:145], v[182:185], v[90:93]
	v_mfma_f32_16x16x32_bf16 v[78:81], v[110:113], v[186:189], v[78:81]
	v_mfma_f32_16x16x32_bf16 v[74:77], v[138:141], v[186:189], v[74:77]
	v_mfma_f32_16x16x32_bf16 v[78:81], v[118:121], v[190:193], v[78:81]
	v_mfma_f32_16x16x32_bf16 v[74:77], v[142:145], v[190:193], v[74:77]
	s_setprio 0
	s_setprio 1
	v_mfma_f32_16x16x32_bf16 v[126:129], v[146:149], v[162:165], v[126:129]
	v_mfma_f32_16x16x32_bf16 v[122:125], v[154:157], v[162:165], v[122:125]
	v_mfma_f32_16x16x32_bf16 v[126:129], v[150:153], v[166:169], v[126:129]
	v_mfma_f32_16x16x32_bf16 v[122:125], v[158:161], v[166:169], v[122:125]
	v_mfma_f32_16x16x32_bf16 v[102:105], v[146:149], v[170:173], v[102:105]
	v_mfma_f32_16x16x32_bf16 v[98:101], v[154:157], v[170:173], v[98:101]
	v_mfma_f32_16x16x32_bf16 v[102:105], v[150:153], v[174:177], v[102:105]
	v_mfma_f32_16x16x32_bf16 v[98:101], v[158:161], v[174:177], v[98:101]
	v_mfma_f32_16x16x32_bf16 v[86:89], v[146:149], v[178:181], v[86:89]
	v_mfma_f32_16x16x32_bf16 v[82:85], v[154:157], v[178:181], v[82:85]
	v_mfma_f32_16x16x32_bf16 v[86:89], v[150:153], v[182:185], v[86:89]
	v_mfma_f32_16x16x32_bf16 v[82:85], v[158:161], v[182:185], v[82:85]
	v_mfma_f32_16x16x32_bf16 v[70:73], v[146:149], v[186:189], v[70:73]
	v_mfma_f32_16x16x32_bf16 v[66:69], v[154:157], v[186:189], v[66:69]
	v_mfma_f32_16x16x32_bf16 v[70:73], v[150:153], v[190:193], v[70:73]
	v_mfma_f32_16x16x32_bf16 v[66:69], v[158:161], v[190:193], v[66:69]
	s_setprio 0
	s_barrier
; #define PG8_STAGE(bufoff, gbase, voff) do { _Pragma("unroll") for (int _i = 0; _i < 2; ++_i) \
;         __builtin_amdgcn_global_load_lds((const unsigned*)((const char*)(gbase) + (voff)[_i]), (PG8_LAS unsigned*)(lds + (bufoff) + ldsw + _i * 8192), 16, 0, 0); } while (0)
; #define PG8_LDA(dst, b, h) do { _Pragma("unroll") for (int m = 0; m < 4; ++m) _Pragma("unroll") for (int k = 0; k < 2; ++k) dst[m][k] = *(const PG8_LAS bf16x8*)(lds + PG8_SA(b, h) + aoff + m * 2048 + k * 1024); } while (0)
; #define PG8_MMA(ai, bj, At, Bt) do { __builtin_amdgcn_s_setprio(1); _Pragma("unroll") for (int m = 0; m < 4; ++m) _Pragma("unroll") for (int n = 0; n < 2; ++n) _Pragma("unroll") for (int k = 0; k < 2; ++k) \
;         acc[ai][bj][m][n] = __builtin_amdgcn_mfma_f32_16x16x32_bf16(Bt[n][k], At[m][k], acc[ai][bj][m][n], 0, 0, 0); __builtin_amdgcn_s_setprio(0); } while (0)
; #define PG8_WAIT_V(n) asm volatile("s_waitcnt vmcnt(" #n ")" ::: "memory")
; #define PG8_WAIT_L(n) asm volatile("s_waitcnt lgkmcnt(" #n ")" ::: "memory")
; #define PG8_BAR __builtin_amdgcn_s_barrier()
; #define PG8_SCHED __builtin_amdgcn_sched_barrier(0)
; template <class Epi, class Sched, bool ALIGN_EPI = false, bool SP2 = false>
; __device__ __forceinline__ void gemm_phase(PG8_LAS unsigned char* lds, const Gemm g, const Sched& S, const Epi& E) {
;     ...
;             PG8_LDA(At, 1, 1); PG8_STAGE(PG8_SB(1, 0), b3, voffB); PG8_STAGE(PG8_SB(1, 1), b3 + hstep, voffB); PG8_STAGE(PG8_SA(1, 0), a3, voffA);
;             PG8_WAIT_V(8); PG8_WAIT_L(0); PG8_BAR; PG8_MMA(1, 0, At, B0); PG8_MMA(1, 1, At, B1); PG8_BAR; PG8_SCHED;
	s_add_i32 s18, s18, s6
	v_lshl_add_u64 v[210:211], v[210:211], 0, s[30:31]
	s_mov_b32 m0, s18
	ds_read_b128 v[162:165], v247 offset:49152
	ds_read_b128 v[166:169], v247 offset:50176
	ds_read_b128 v[170:173], v247 offset:51200
	ds_read_b128 v[174:177], v247 offset:52224
	ds_read_b128 v[178:181], v247 offset:53248
	ds_read_b128 v[182:185], v247 offset:54272
	ds_read_b128 v[186:189], v247 offset:55296
	ds_read_b128 v[190:193], v247 offset:56320
	global_load_lds_dwordx4 v[210:211], off
	v_lshl_add_u64 v[210:211], v[212:213], 0, s[30:31]
	s_add_i32 m0, s18, 0x2000
	s_add_i32 s18, vcc_hi, s6
	global_load_lds_dwordx4 v[210:211], off
	v_lshl_add_u64 v[210:211], v[214:215], 0, s[30:31]
	s_mov_b32 m0, s18
	s_nop 0
	global_load_lds_dwordx4 v[210:211], off
	v_lshl_add_u64 v[210:211], v[216:217], 0, s[30:31]
	s_add_i32 m0, s18, 0x2000
	s_nop 0
	global_load_lds_dwordx4 v[210:211], off
	v_lshl_add_u64 v[210:211], v[218:219], 0, s[30:31]
	s_mov_b32 m0, s97
	s_nop 0
	global_load_lds_dwordx4 v[210:211], off
	v_lshl_add_u64 v[210:211], v[220:221], 0, s[30:31]
	s_mov_b32 m0, s98
	s_nop 0
	global_load_lds_dwordx4 v[210:211], off
	s_waitcnt vmcnt(8)
	s_waitcnt lgkmcnt(0)
	s_barrier
	s_setprio 1
	s_waitcnt lgkmcnt(0)
	v_mfma_f32_16x16x32_bf16 v[62:65], v[110:113], v[162:165], v[62:65]
	v_mfma_f32_16x16x32_bf16 v[58:61], v[138:141], v[162:165], v[58:61]
	v_mfma_f32_16x16x32_bf16 v[62:65], v[118:121], v[166:169], v[62:65]
	v_mfma_f32_16x16x32_bf16 v[58:61], v[142:145], v[166:169], v[58:61]
	v_mfma_f32_16x16x32_bf16 v[46:49], v[110:113], v[170:173], v[46:49]
	v_mfma_f32_16x16x32_bf16 v[42:45], v[138:141], v[170:173], v[42:45]
	v_mfma_f32_16x16x32_bf16 v[46:49], v[118:121], v[174:177], v[46:49]
	v_mfma_f32_16x16x32_bf16 v[42:45], v[142:145], v[174:177], v[42:45]
	v_mfma_f32_16x16x32_bf16 v[30:33], v[110:113], v[178:181], v[30:33]
	v_mfma_f32_16x16x32_bf16 v[26:29], v[138:141], v[178:181], v[26:29]
	v_mfma_f32_16x16x32_bf16 v[30:33], v[118:121], v[182:185], v[30:33]
	v_mfma_f32_16x16x32_bf16 v[26:29], v[142:145], v[182:185], v[26:29]
	v_mfma_f32_16x16x32_bf16 v[14:17], v[110:113], v[186:189], v[14:17]
	v_mfma_f32_16x16x32_bf16 v[10:13], v[138:141], v[186:189], v[10:13]
	v_mfma_f32_16x16x32_bf16 v[14:17], v[118:121], v[190:193], v[14:17]
	v_mfma_f32_16x16x32_bf16 v[10:13], v[142:145], v[190:193], v[10:13]
	s_setprio 0
	s_setprio 1
	v_mfma_f32_16x16x32_bf16 v[54:57], v[146:149], v[162:165], v[54:57]
	v_mfma_f32_16x16x32_bf16 v[50:53], v[154:157], v[162:165], v[50:53]
	v_mfma_f32_16x16x32_bf16 v[54:57], v[150:153], v[166:169], v[54:57]
	v_mfma_f32_16x16x32_bf16 v[50:53], v[158:161], v[166:169], v[50:53]
	v_mfma_f32_16x16x32_bf16 v[38:41], v[146:149], v[170:173], v[38:41]
	v_mfma_f32_16x16x32_bf16 v[34:37], v[154:157], v[170:173], v[34:37]
	v_mfma_f32_16x16x32_bf16 v[38:41], v[150:153], v[174:177], v[38:41]
	v_mfma_f32_16x16x32_bf16 v[34:37], v[158:161], v[174:177], v[34:37]
	v_mfma_f32_16x16x32_bf16 v[22:25], v[146:149], v[178:181], v[22:25]
	v_mfma_f32_16x16x32_bf16 v[18:21], v[154:157], v[178:181], v[18:21]
	v_mfma_f32_16x16x32_bf16 v[22:25], v[150:153], v[182:185], v[22:25]
	v_mfma_f32_16x16x32_bf16 v[18:21], v[158:161], v[182:185], v[18:21]
	v_mfma_f32_16x16x32_bf16 v[6:9], v[146:149], v[186:189], v[6:9]
	v_mfma_f32_16x16x32_bf16 v[2:5], v[154:157], v[186:189], v[2:5]
	v_mfma_f32_16x16x32_bf16 v[6:9], v[150:153], v[190:193], v[6:9]
	v_mfma_f32_16x16x32_bf16 v[2:5], v[158:161], v[190:193], v[2:5]
	s_setprio 0
	s_barrier
	s_add_u32 s48, s48, 0x100
	s_addc_u32 s49, s49, 0
	s_add_u32 s50, s50, 0x100
	s_addc_u32 s51, s51, 0
	s_cmp_ge_u32 vcc_lo, s96
	s_mov_b32 s46, vcc_lo
	s_cbranch_scc0 .LBB0_274
	s_and_b64 vcc, exec, s[72:73]
	s_cbranch_vccz .LBB0_277
	s_barrier

; #define PG8_STAGE(bufoff, gbase, voff) do { _Pragma("unroll") for (int _i = 0; _i < 2; ++_i) \
;         __builtin_amdgcn_global_load_lds((const unsigned*)((const char*)(gbase) + (voff)[_i]), (PG8_LAS unsigned*)(lds + (bufoff) + ldsw + _i * 8192), 16, 0, 0); } while (0)
; #define PG8_LDA(dst, b, h) do { _Pragma("unroll") for (int m = 0; m < 4; ++m) _Pragma("unroll") for (int k = 0; k < 2; ++k) dst[m][k] = *(const PG8_LAS bf16x8*)(lds + PG8_SA(b, h) + aoff + m * 2048 + k * 1024); } while (0)
; #define PG8_LDB(dst, b, h) do { _Pragma("unroll") for (int n = 0; n < 2; ++n) _Pragma("unroll") for (int k = 0; k < 2; ++k) dst[n][k] = *(const PG8_LAS bf16x8*)(lds + PG8_SB(b, h) + boff + n * 2048 + k * 1024); } while (0)
; #define PG8_MMA(ai, bj, At, Bt) do { __builtin_amdgcn_s_setprio(1); _Pragma("unroll") for (int m = 0; m < 4; ++m) _Pragma("unroll") for (int n = 0; n < 2; ++n) _Pragma("unroll") for (int k = 0; k < 2; ++k) \
;         acc[ai][bj][m][n] = __builtin_amdgcn_mfma_f32_16x16x32_bf16(Bt[n][k], At[m][k], acc[ai][bj][m][n], 0, 0, 0); __builtin_amdgcn_s_setprio(0); } while (0)
; #define PG8_WAIT_V(n) asm volatile("s_waitcnt vmcnt(" #n ")" ::: "memory")
; #define PG8_WAIT_L(n) asm volatile("s_waitcnt lgkmcnt(" #n ")" ::: "memory")
; #define PG8_BAR __builtin_amdgcn_s_barrier()
; #define PG8_SCHED __builtin_amdgcn_sched_barrier(0)
; template <class Epi, class Sched, bool ALIGN_EPI = false, bool SP2 = false>
; __device__ __forceinline__ void gemm_phase(PG8_LAS unsigned char* lds, const Gemm g, const Sched& S, const Epi& E) {
;     ...
;             const bool last = (t == nt - 2);
;             const char* a1 = cA + (size_t)(t + 1) * kstep;
;             const char* a2 = last ? nA : cA + (size_t)(t + 2) * kstep; const char* b2 = last ? nB : cB + (size_t)(t + 2) * kstep;
;             const char* a3 = a2 + kstep; const char* b3 = b2 + kstep;
;             if (last && has_next) S.a_ready(nxt);
;             if constexpr (SP2) {
;             PG8_LDB(B0, 0, 0); PG8_LDB(B1, 0, 1); PG8_SCHED; PG8_LDA(At, 0, 0); PG8_STAGE(PG8_SA(1, 1), a1 + hstep, voffA);
;             PG8_WAIT_V(8); PG8_WAIT_L(0); PG8_BAR; PG8_MMA(0, 0, At, B0); PG8_MMA(0, 1, At, B1); PG8_BAR; PG8_SCHED;
;             PG8_LDA(At, 0, 1); PG8_STAGE(PG8_SB(0, 0), b2, voffB); PG8_STAGE(PG8_SB(0, 1), b2 + hstep, voffB); PG8_STAGE(PG8_SA(0, 0), a2, voffA);
.LBB0_408:
	s_add_u32 s38, s48, 0xfffc0080
	s_addc_u32 s39, s49, -1
	s_add_i32 s85, 0, 0x10000
	s_cmp_eq_u32 s84, 12
	s_cselect_b32 s73, s21, s39
	s_cselect_b32 s72, s27, s38
	v_add_u32_e32 v0, s85, v167
	s_cselect_b32 s47, s29, s69
	s_cselect_b32 s46, s33, s53
	s_add_i32 s38, 0, 0x14000
	ds_read_b128 v[142:145], v0
	ds_read_b128 v[146:149], v0 offset:1024
	ds_read_b128 v[150:153], v0 offset:2048
	ds_read_b128 v[154:157], v0 offset:3072
	v_add_u32_e32 v0, s38, v167
	ds_read_b128 v[158:161], v0
	ds_read_b128 v[162:165], v0 offset:1024
	ds_read_b128 v[172:175], v0 offset:2048
	ds_read_b128 v[176:179], v0 offset:3072
	v_lshl_add_u64 v[218:219], s[48:49], 0, v[138:139]
	s_add_i32 m0, s76, 0xc000
	ds_read_b128 v[180:183], v170
	ds_read_b128 v[184:187], v170 offset:1024
	ds_read_b128 v[188:191], v170 offset:2048
	ds_read_b128 v[192:195], v170 offset:3072
	ds_read_b128 v[202:205], v170 offset:4096
	ds_read_b128 v[206:209], v170 offset:5120
	ds_read_b128 v[210:213], v170 offset:6144
	ds_read_b128 v[214:217], v170 offset:7168
	global_load_lds_dwordx4 v[218:219], off
	v_lshl_add_u64 v[218:219], s[48:49], 0, v[140:141]
	s_add_i32 m0, s76, 0xe000
	s_nop 0
	global_load_lds_dwordx4 v[218:219], off
	s_waitcnt vmcnt(8)
	s_waitcnt lgkmcnt(0)
	s_barrier
	s_setprio 1
	s_waitcnt lgkmcnt(0)
	v_mfma_f32_16x16x32_bf16 v[122:125], v[142:145], v[180:183], v[122:125]
	v_mfma_f32_16x16x32_bf16 v[126:129], v[150:153], v[180:183], v[126:129]
	v_mfma_f32_16x16x32_bf16 v[122:125], v[146:149], v[184:187], v[122:125]
	v_mfma_f32_16x16x32_bf16 v[126:129], v[154:157], v[184:187], v[126:129]
	v_mfma_f32_16x16x32_bf16 v[106:109], v[142:145], v[188:191], v[106:109]
	v_mfma_f32_16x16x32_bf16 v[110:113], v[150:153], v[188:191], v[110:113]
	v_mfma_f32_16x16x32_bf16 v[106:109], v[146:149], v[192:195], v[106:109]
	v_mfma_f32_16x16x32_bf16 v[110:113], v[154:157], v[192:195], v[110:113]
	v_mfma_f32_16x16x32_bf16 v[90:93], v[142:145], v[202:205], v[90:93]
	v_mfma_f32_16x16x32_bf16 v[94:97], v[150:153], v[202:205], v[94:97]
	v_mfma_f32_16x16x32_bf16 v[90:93], v[146:149], v[206:209], v[90:93]
	v_mfma_f32_16x16x32_bf16 v[94:97], v[154:157], v[206:209], v[94:97]
	v_mfma_f32_16x16x32_bf16 v[74:77], v[142:145], v[210:213], v[74:77]
	v_mfma_f32_16x16x32_bf16 v[78:81], v[150:153], v[210:213], v[78:81]
	v_mfma_f32_16x16x32_bf16 v[74:77], v[146:149], v[214:217], v[74:77]
	v_mfma_f32_16x16x32_bf16 v[78:81], v[154:157], v[214:217], v[78:81]
	s_setprio 0
	s_setprio 1
	v_mfma_f32_16x16x32_bf16 v[114:117], v[158:161], v[180:183], v[114:117]
	v_mfma_f32_16x16x32_bf16 v[118:121], v[172:175], v[180:183], v[118:121]
	v_mfma_f32_16x16x32_bf16 v[114:117], v[162:165], v[184:187], v[114:117]
	v_mfma_f32_16x16x32_bf16 v[118:121], v[176:179], v[184:187], v[118:121]
	v_mfma_f32_16x16x32_bf16 v[98:101], v[158:161], v[188:191], v[98:101]
	v_mfma_f32_16x16x32_bf16 v[102:105], v[172:175], v[188:191], v[102:105]
	v_mfma_f32_16x16x32_bf16 v[98:101], v[162:165], v[192:195], v[98:101]
	v_mfma_f32_16x16x32_bf16 v[102:105], v[176:179], v[192:195], v[102:105]
	v_mfma_f32_16x16x32_bf16 v[82:85], v[158:161], v[202:205], v[82:85]
	v_mfma_f32_16x16x32_bf16 v[86:89], v[172:175], v[202:205], v[86:89]
	v_mfma_f32_16x16x32_bf16 v[82:85], v[162:165], v[206:209], v[82:85]
	v_mfma_f32_16x16x32_bf16 v[86:89], v[176:179], v[206:209], v[86:89]
	v_mfma_f32_16x16x32_bf16 v[66:69], v[158:161], v[210:213], v[66:69]
	v_mfma_f32_16x16x32_bf16 v[70:73], v[172:175], v[210:213], v[70:73]
	v_mfma_f32_16x16x32_bf16 v[66:69], v[162:165], v[214:217], v[66:69]
	v_mfma_f32_16x16x32_bf16 v[70:73], v[176:179], v[214:217], v[70:73]
	s_setprio 0
	s_barrier
	s_add_i32 s39, s85, s75
	v_lshl_add_u64 v[218:219], s[46:47], 0, v[134:135]
	s_mov_b32 m0, s39
	ds_read_b128 v[180:183], v170 offset:16384
	ds_read_b128 v[184:187], v170 offset:17408
	ds_read_b128 v[188:191], v170 offset:18432
	ds_read_b128 v[192:195], v170 offset:19456
	ds_read_b128 v[202:205], v170 offset:20480
	ds_read_b128 v[206:209], v170 offset:21504
	ds_read_b128 v[210:213], v170 offset:22528
	ds_read_b128 v[214:217], v170 offset:23552
	global_load_lds_dwordx4 v[218:219], off
	s_add_i32 m0, s39, 0x2000
	s_add_u32 s92, s46, 0x40000
	v_lshl_add_u64 v[220:221], s[46:47], 0, v[130:131]
	s_addc_u32 s93, s47, 0
	s_add_i32 s38, s38, s75
	global_load_lds_dwordx4 v[220:221], off
	v_lshl_add_u64 v[222:223], s[92:93], 0, v[134:135]
	s_mov_b32 m0, s38
	v_lshl_add_u64 v[224:225], s[72:73], 0, v[132:133]
	global_load_lds_dwordx4 v[222:223], off
	v_lshl_add_u64 v[222:223], s[92:93], 0, v[130:131]
	s_add_i32 m0, s38, 0x2000
	s_nop 0
	global_load_lds_dwordx4 v[222:223], off
	v_lshl_add_u64 v[222:223], s[72:73], 0, v[136:137]
	s_mov_b32 m0, s76
	s_nop 0
	global_load_lds_dwordx4 v[222:223], off
	s_mov_b32 m0, s77
	s_nop 0
	global_load_lds_dwordx4 v[224:225], off
	s_waitcnt vmcnt(8)
	s_waitcnt lgkmcnt(0)
	s_barrier
; #define PG8_STAGE(bufoff, gbase, voff) do { _Pragma("unroll") for (int _i = 0; _i < 2; ++_i) \
;         __builtin_amdgcn_global_load_lds((const unsigned*)((const char*)(gbase) + (voff)[_i]), (PG8_LAS unsigned*)(lds + (bufoff) + ldsw + _i * 8192), 16, 0, 0); } while (0)
; #define PG8_LDA(dst, b, h) do { _Pragma("unroll") for (int m = 0; m < 4; ++m) _Pragma("unroll") for (int k = 0; k < 2; ++k) dst[m][k] = *(const PG8_LAS bf16x8*)(lds + PG8_SA(b, h) + aoff + m * 2048 + k * 1024); } while (0)
; #define PG8_LDB(dst, b, h) do { _Pragma("unroll") for (int n = 0; n < 2; ++n) _Pragma("unroll") for (int k = 0; k < 2; ++k) dst[n][k] = *(const PG8_LAS bf16x8*)(lds + PG8_SB(b, h) + boff + n * 2048 + k * 1024); } while (0)
; #define PG8_MMA(ai, bj, At, Bt) do { __builtin_amdgcn_s_setprio(1); _Pragma("unroll") for (int m = 0; m < 4; ++m) _Pragma("unroll") for (int n = 0; n < 2; ++n) _Pragma("unroll") for (int k = 0; k < 2; ++k) \
;         acc[ai][bj][m][n] = __builtin_amdgcn_mfma_f32_16x16x32_bf16(Bt[n][k], At[m][k], acc[ai][bj][m][n], 0, 0, 0); __builtin_amdgcn_s_setprio(0); } while (0)
; #define PG8_WAIT_V(n) asm volatile("s_waitcnt vmcnt(" #n ")" ::: "memory")
; #define PG8_WAIT_L(n) asm volatile("s_waitcnt lgkmcnt(" #n ")" ::: "memory")
; #define PG8_BAR __builtin_amdgcn_s_barrier()
; #define PG8_SCHED __builtin_amdgcn_sched_barrier(0)
; template <class Epi, class Sched, bool ALIGN_EPI = false, bool SP2 = false>
; __device__ __forceinline__ void gemm_phase(PG8_LAS unsigned char* lds, const Gemm g, const Sched& S, const Epi& E) {
;     ...
;             PG8_WAIT_V(8); PG8_WAIT_L(0); PG8_BAR; PG8_MMA(1, 0, At, B0); PG8_MMA(1, 1, At, B1); PG8_BAR; PG8_SCHED;
;             PG8_LDB(B0, 1, 0); PG8_LDB(B1, 1, 1); PG8_SCHED; PG8_LDA(At, 1, 0); PG8_STAGE(PG8_SA(0, 1), a2 + hstep, voffA);
;             PG8_WAIT_V(8); PG8_WAIT_L(0); PG8_BAR; PG8_MMA(0, 0, At, B0); PG8_MMA(0, 1, At, B1); PG8_BAR; PG8_SCHED;
	s_setprio 1
	s_waitcnt lgkmcnt(0)
	v_mfma_f32_16x16x32_bf16 v[58:61], v[142:145], v[180:183], v[58:61]
	v_mfma_f32_16x16x32_bf16 v[62:65], v[150:153], v[180:183], v[62:65]
	v_mfma_f32_16x16x32_bf16 v[58:61], v[146:149], v[184:187], v[58:61]
	v_mfma_f32_16x16x32_bf16 v[62:65], v[154:157], v[184:187], v[62:65]
	v_mfma_f32_16x16x32_bf16 v[42:45], v[142:145], v[188:191], v[42:45]
	v_mfma_f32_16x16x32_bf16 v[46:49], v[150:153], v[188:191], v[46:49]
	v_mfma_f32_16x16x32_bf16 v[42:45], v[146:149], v[192:195], v[42:45]
	v_mfma_f32_16x16x32_bf16 v[46:49], v[154:157], v[192:195], v[46:49]
	v_mfma_f32_16x16x32_bf16 v[26:29], v[142:145], v[202:205], v[26:29]
	v_mfma_f32_16x16x32_bf16 v[30:33], v[150:153], v[202:205], v[30:33]
	v_mfma_f32_16x16x32_bf16 v[26:29], v[146:149], v[206:209], v[26:29]
	v_mfma_f32_16x16x32_bf16 v[30:33], v[154:157], v[206:209], v[30:33]
	v_mfma_f32_16x16x32_bf16 v[10:13], v[142:145], v[210:213], v[10:13]
	v_mfma_f32_16x16x32_bf16 v[14:17], v[150:153], v[210:213], v[14:17]
	v_mfma_f32_16x16x32_bf16 v[10:13], v[146:149], v[214:217], v[10:13]
	v_mfma_f32_16x16x32_bf16 v[14:17], v[154:157], v[214:217], v[14:17]
	s_setprio 0
	s_setprio 1
	v_mfma_f32_16x16x32_bf16 v[50:53], v[158:161], v[180:183], v[50:53]
	v_mfma_f32_16x16x32_bf16 v[54:57], v[172:175], v[180:183], v[54:57]
	v_mfma_f32_16x16x32_bf16 v[50:53], v[162:165], v[184:187], v[50:53]
	v_mfma_f32_16x16x32_bf16 v[54:57], v[176:179], v[184:187], v[54:57]
	v_mfma_f32_16x16x32_bf16 v[34:37], v[158:161], v[188:191], v[34:37]
	v_mfma_f32_16x16x32_bf16 v[38:41], v[172:175], v[188:191], v[38:41]
	v_mfma_f32_16x16x32_bf16 v[34:37], v[162:165], v[192:195], v[34:37]
	v_mfma_f32_16x16x32_bf16 v[38:41], v[176:179], v[192:195], v[38:41]
	v_mfma_f32_16x16x32_bf16 v[18:21], v[158:161], v[202:205], v[18:21]
	v_mfma_f32_16x16x32_bf16 v[22:25], v[172:175], v[202:205], v[22:25]
	v_mfma_f32_16x16x32_bf16 v[18:21], v[162:165], v[206:209], v[18:21]
	v_mfma_f32_16x16x32_bf16 v[22:25], v[176:179], v[206:209], v[22:25]
	v_mfma_f32_16x16x32_bf16 v[2:5], v[158:161], v[210:213], v[2:5]
	v_mfma_f32_16x16x32_bf16 v[6:9], v[172:175], v[210:213], v[6:9]
	v_mfma_f32_16x16x32_bf16 v[2:5], v[162:165], v[214:217], v[2:5]
	v_mfma_f32_16x16x32_bf16 v[6:9], v[176:179], v[214:217], v[6:9]
	s_setprio 0
	s_barrier
	s_add_i32 s38, 0, 0x18000
	v_add_u32_e32 v0, s38, v167
	s_add_i32 s39, 0, 0x1c000
	ds_read_b128 v[142:145], v0
	ds_read_b128 v[146:149], v0 offset:1024
	ds_read_b128 v[150:153], v0 offset:2048
	ds_read_b128 v[154:157], v0 offset:3072
	v_add_u32_e32 v0, s39, v167
	ds_read_b128 v[158:161], v0
	ds_read_b128 v[162:165], v0 offset:1024
	ds_read_b128 v[172:175], v0 offset:2048
	ds_read_b128 v[176:179], v0 offset:3072
	s_add_u32 s72, s72, 0x40000
	s_addc_u32 s73, s73, 0
	s_mov_b32 m0, s78
	v_lshl_add_u64 v[226:227], s[72:73], 0, v[136:137]
	ds_read_b128 v[180:183], v170 offset:32768
	ds_read_b128 v[184:187], v170 offset:33792
	ds_read_b128 v[188:191], v170 offset:34816
	ds_read_b128 v[192:195], v170 offset:35840
	ds_read_b128 v[202:205], v170 offset:36864
	ds_read_b128 v[206:209], v170 offset:37888
	ds_read_b128 v[210:213], v170 offset:38912
	ds_read_b128 v[214:217], v170 offset:39936
	global_load_lds_dwordx4 v[226:227], off
	v_lshl_add_u64 v[226:227], s[72:73], 0, v[132:133]
	s_mov_b32 m0, s79
	s_nop 0
	global_load_lds_dwordx4 v[226:227], off
	s_waitcnt vmcnt(8)
	s_waitcnt lgkmcnt(0)
	s_barrier
	s_setprio 1
	s_waitcnt lgkmcnt(0)
	v_mfma_f32_16x16x32_bf16 v[122:125], v[142:145], v[180:183], v[122:125]
	v_mfma_f32_16x16x32_bf16 v[126:129], v[150:153], v[180:183], v[126:129]
	v_mfma_f32_16x16x32_bf16 v[122:125], v[146:149], v[184:187], v[122:125]
	v_mfma_f32_16x16x32_bf16 v[126:129], v[154:157], v[184:187], v[126:129]
	v_mfma_f32_16x16x32_bf16 v[106:109], v[142:145], v[188:191], v[106:109]
	v_mfma_f32_16x16x32_bf16 v[110:113], v[150:153], v[188:191], v[110:113]
	v_mfma_f32_16x16x32_bf16 v[106:109], v[146:149], v[192:195], v[106:109]
	v_mfma_f32_16x16x32_bf16 v[110:113], v[154:157], v[192:195], v[110:113]
	v_mfma_f32_16x16x32_bf16 v[90:93], v[142:145], v[202:205], v[90:93]
	v_mfma_f32_16x16x32_bf16 v[94:97], v[150:153], v[202:205], v[94:97]
	v_mfma_f32_16x16x32_bf16 v[90:93], v[146:149], v[206:209], v[90:93]
	v_mfma_f32_16x16x32_bf16 v[94:97], v[154:157], v[206:209], v[94:97]
	v_mfma_f32_16x16x32_bf16 v[74:77], v[142:145], v[210:213], v[74:77]
	v_mfma_f32_16x16x32_bf16 v[78:81], v[150:153], v[210:213], v[78:81]
	v_mfma_f32_16x16x32_bf16 v[74:77], v[146:149], v[214:217], v[74:77]
	v_mfma_f32_16x16x32_bf16 v[78:81], v[154:157], v[214:217], v[78:81]
	s_setprio 0
	s_setprio 1
	v_mfma_f32_16x16x32_bf16 v[114:117], v[158:161], v[180:183], v[114:117]
	v_mfma_f32_16x16x32_bf16 v[118:121], v[172:175], v[180:183], v[118:121]
	v_mfma_f32_16x16x32_bf16 v[114:117], v[162:165], v[184:187], v[114:117]
	v_mfma_f32_16x16x32_bf16 v[118:121], v[176:179], v[184:187], v[118:121]
	v_mfma_f32_16x16x32_bf16 v[98:101], v[158:161], v[188:191], v[98:101]
	v_mfma_f32_16x16x32_bf16 v[102:105], v[172:175], v[188:191], v[102:105]
	v_mfma_f32_16x16x32_bf16 v[98:101], v[162:165], v[192:195], v[98:101]
	v_mfma_f32_16x16x32_bf16 v[102:105], v[176:179], v[192:195], v[102:105]
	v_mfma_f32_16x16x32_bf16 v[82:85], v[158:161], v[202:205], v[82:85]
	v_mfma_f32_16x16x32_bf16 v[86:89], v[172:175], v[202:205], v[86:89]
	v_mfma_f32_16x16x32_bf16 v[82:85], v[162:165], v[206:209], v[82:85]
	v_mfma_f32_16x16x32_bf16 v[86:89], v[176:179], v[206:209], v[86:89]
	v_mfma_f32_16x16x32_bf16 v[66:69], v[158:161], v[210:213], v[66:69]
	v_mfma_f32_16x16x32_bf16 v[70:73], v[172:175], v[210:213], v[70:73]
	v_mfma_f32_16x16x32_bf16 v[66:69], v[162:165], v[214:217], v[66:69]
	v_mfma_f32_16x16x32_bf16 v[70:73], v[176:179], v[214:217], v[70:73]
	s_setprio 0
	s_barrier
; #define PG8_STAGE(bufoff, gbase, voff) do { _Pragma("unroll") for (int _i = 0; _i < 2; ++_i) \
;         __builtin_amdgcn_global_load_lds((const unsigned*)((const char*)(gbase) + (voff)[_i]), (PG8_LAS unsigned*)(lds + (bufoff) + ldsw + _i * 8192), 16, 0, 0); } while (0)
; #define PG8_LDA(dst, b, h) do { _Pragma("unroll") for (int m = 0; m < 4; ++m) _Pragma("unroll") for (int k = 0; k < 2; ++k) dst[m][k] = *(const PG8_LAS bf16x8*)(lds + PG8_SA(b, h) + aoff + m * 2048 + k * 1024); } while (0)
; #define PG8_MMA(ai, bj, At, Bt) do { __builtin_amdgcn_s_setprio(1); _Pragma("unroll") for (int m = 0; m < 4; ++m) _Pragma("unroll") for (int n = 0; n < 2; ++n) _Pragma("unroll") for (int k = 0; k < 2; ++k) \
;         acc[ai][bj][m][n] = __builtin_amdgcn_mfma_f32_16x16x32_bf16(Bt[n][k], At[m][k], acc[ai][bj][m][n], 0, 0, 0); __builtin_amdgcn_s_setprio(0); } while (0)
; #define PG8_WAIT_V(n) asm volatile("s_waitcnt vmcnt(" #n ")" ::: "memory")
; #define PG8_WAIT_L(n) asm volatile("s_waitcnt lgkmcnt(" #n ")" ::: "memory")
; #define PG8_BAR __builtin_amdgcn_s_barrier()
; #define PG8_SCHED __builtin_amdgcn_sched_barrier(0)
; template <class Epi, class Sched, bool ALIGN_EPI = false, bool SP2 = false>
; __device__ __forceinline__ void gemm_phase(PG8_LAS unsigned char* lds, const Gemm g, const Sched& S, const Epi& E) {
;     ...
;             PG8_LDA(At, 1, 1); PG8_STAGE(PG8_SB(1, 0), b3, voffB); PG8_STAGE(PG8_SB(1, 1), b3 + hstep, voffB); PG8_STAGE(PG8_SA(1, 0), a3, voffA);
;             PG8_WAIT_V(8); PG8_WAIT_L(0); PG8_BAR; PG8_MMA(1, 0, At, B0); PG8_MMA(1, 1, At, B1); PG8_BAR; PG8_SCHED;
	s_add_i32 s38, s38, s75
	v_lshl_add_u64 v[218:219], v[218:219], 0, s[30:31]
	s_mov_b32 m0, s38
	ds_read_b128 v[180:183], v170 offset:49152
	ds_read_b128 v[184:187], v170 offset:50176
	ds_read_b128 v[188:191], v170 offset:51200
	ds_read_b128 v[192:195], v170 offset:52224
	ds_read_b128 v[202:205], v170 offset:53248
	ds_read_b128 v[206:209], v170 offset:54272
	ds_read_b128 v[210:213], v170 offset:55296
	ds_read_b128 v[214:217], v170 offset:56320
	global_load_lds_dwordx4 v[218:219], off
	s_add_i32 m0, s38, 0x2000
	s_add_u32 s46, s46, 0x40080
	v_lshl_add_u64 v[218:219], v[220:221], 0, s[30:31]
	s_addc_u32 s47, s47, 0
	s_add_i32 s38, s39, s75
	global_load_lds_dwordx4 v[218:219], off
	v_lshl_add_u64 v[218:219], s[46:47], 0, v[134:135]
	s_mov_b32 m0, s38
	s_nop 0
	global_load_lds_dwordx4 v[218:219], off
	v_lshl_add_u64 v[218:219], s[46:47], 0, v[130:131]
	s_add_i32 m0, s38, 0x2000
	s_nop 0
	global_load_lds_dwordx4 v[218:219], off
	v_lshl_add_u64 v[218:219], v[222:223], 0, s[30:31]
	s_mov_b32 m0, s80
	s_nop 0
	global_load_lds_dwordx4 v[218:219], off
	v_lshl_add_u64 v[218:219], v[224:225], 0, s[30:31]
	s_mov_b32 m0, s81
	s_nop 0
	global_load_lds_dwordx4 v[218:219], off
	s_waitcnt vmcnt(8)
	s_waitcnt lgkmcnt(0)
	s_barrier
	s_setprio 1
	s_waitcnt lgkmcnt(0)
	v_mfma_f32_16x16x32_bf16 v[58:61], v[142:145], v[180:183], v[58:61]
	v_mfma_f32_16x16x32_bf16 v[62:65], v[150:153], v[180:183], v[62:65]
	v_mfma_f32_16x16x32_bf16 v[58:61], v[146:149], v[184:187], v[58:61]
	v_mfma_f32_16x16x32_bf16 v[62:65], v[154:157], v[184:187], v[62:65]
	v_mfma_f32_16x16x32_bf16 v[42:45], v[142:145], v[188:191], v[42:45]
	v_mfma_f32_16x16x32_bf16 v[46:49], v[150:153], v[188:191], v[46:49]
	v_mfma_f32_16x16x32_bf16 v[42:45], v[146:149], v[192:195], v[42:45]
	v_mfma_f32_16x16x32_bf16 v[46:49], v[154:157], v[192:195], v[46:49]
	v_mfma_f32_16x16x32_bf16 v[26:29], v[142:145], v[202:205], v[26:29]
	v_mfma_f32_16x16x32_bf16 v[30:33], v[150:153], v[202:205], v[30:33]
	v_mfma_f32_16x16x32_bf16 v[26:29], v[146:149], v[206:209], v[26:29]
	v_mfma_f32_16x16x32_bf16 v[30:33], v[154:157], v[206:209], v[30:33]
	v_mfma_f32_16x16x32_bf16 v[10:13], v[142:145], v[210:213], v[10:13]
	v_mfma_f32_16x16x32_bf16 v[14:17], v[150:153], v[210:213], v[14:17]
	v_mfma_f32_16x16x32_bf16 v[10:13], v[146:149], v[214:217], v[10:13]
	v_mfma_f32_16x16x32_bf16 v[14:17], v[154:157], v[214:217], v[14:17]
	s_setprio 0
	s_setprio 1
	v_mfma_f32_16x16x32_bf16 v[50:53], v[158:161], v[180:183], v[50:53]
	v_mfma_f32_16x16x32_bf16 v[54:57], v[172:175], v[180:183], v[54:57]
	v_mfma_f32_16x16x32_bf16 v[50:53], v[162:165], v[184:187], v[50:53]
	v_mfma_f32_16x16x32_bf16 v[54:57], v[176:179], v[184:187], v[54:57]
	v_mfma_f32_16x16x32_bf16 v[34:37], v[158:161], v[188:191], v[34:37]
	v_mfma_f32_16x16x32_bf16 v[38:41], v[172:175], v[188:191], v[38:41]
	v_mfma_f32_16x16x32_bf16 v[34:37], v[162:165], v[192:195], v[34:37]
	v_mfma_f32_16x16x32_bf16 v[38:41], v[176:179], v[192:195], v[38:41]
	v_mfma_f32_16x16x32_bf16 v[18:21], v[158:161], v[202:205], v[18:21]
	v_mfma_f32_16x16x32_bf16 v[22:25], v[172:175], v[202:205], v[22:25]
	v_mfma_f32_16x16x32_bf16 v[18:21], v[162:165], v[206:209], v[18:21]
	v_mfma_f32_16x16x32_bf16 v[22:25], v[176:179], v[206:209], v[22:25]
	v_mfma_f32_16x16x32_bf16 v[2:5], v[158:161], v[210:213], v[2:5]
	v_mfma_f32_16x16x32_bf16 v[6:9], v[172:175], v[210:213], v[6:9]
	v_mfma_f32_16x16x32_bf16 v[2:5], v[162:165], v[214:217], v[2:5]
	v_mfma_f32_16x16x32_bf16 v[6:9], v[176:179], v[214:217], v[6:9]
	s_setprio 0
	s_barrier
	s_add_i32 s84, s84, 2
	s_add_u32 s48, s48, 0x100
	s_addc_u32 s49, s49, 0
	s_add_u32 s53, s53, 0x100
	s_addc_u32 s69, s69, 0
	s_cmp_gt_u32 s84, 13
	s_cbranch_scc0 .LBB0_408
	s_and_b64 vcc, exec, s[64:65]
	s_cbranch_vccz .LBB0_411
	s_barrier
